# static s_setprio 1 for the younger half (waves 4-7) around every GEMM K-loop, on top of the per-segment setprio removal
# baseline (speedup 1.0000x reference)
; #define PG8_STAGE(bufoff, gbase, voff) do { _Pragma("unroll") for (int _i = 0; _i < 2; ++_i) \
;         __builtin_amdgcn_global_load_lds((const unsigned*)((const char*)(gbase) + (voff)[_i]), (PG8_LAS unsigned*)(lds + (bufoff) + ldsw + _i * 8192), 16, 0, 0); } while (0)
; #define PG8_LDA(dst, b, h) do { _Pragma("unroll") for (int m = 0; m < 4; ++m) _Pragma("unroll") for (int k = 0; k < 2; ++k) dst[m][k] = *(const PG8_LAS bf16x8*)(lds + PG8_SA(b, h) + aoff + m * 2048 + k * 1024); } while (0)
; #define PG8_LDB(dst, b, h) do { _Pragma("unroll") for (int n = 0; n < 2; ++n) _Pragma("unroll") for (int k = 0; k < 2; ++k) dst[n][k] = *(const PG8_LAS bf16x8*)(lds + PG8_SB(b, h) + boff + n * 2048 + k * 1024); } while (0)
; #define PG8_WAIT_V(n) asm volatile("s_waitcnt vmcnt(" #n ")" ::: "memory")
; #define PG8_WAIT_L(n) asm volatile("s_waitcnt lgkmcnt(" #n ")" ::: "memory")
; #define PG8_BAR __builtin_amdgcn_s_barrier()
; template <class Epi, class Sched, bool ALIGN_EPI = false, bool SP2 = false>
; __device__ __forceinline__ void gemm_phase(PG8_LAS unsigned char* lds, const Gemm g, const Sched& S, const Epi& E) {
;     ...
;         const bool has_next = S.next(ui + 1, nxt);
;         const char* nA = has_next ? (const char*)g.A + (size_t)nxt.pm * tstep : cA; const char* nB = has_next ? (const char*)g.Bt + (size_t)nxt.pn * tstep : cB;
;         for (int t = 0; t < nt; t += 2) {
;             const bool last = (t == nt - 2);
;             const char* a1 = cA + (size_t)(t + 1) * kstep;
;             const char* a2 = last ? nA : cA + (size_t)(t + 2) * kstep; const char* b2 = last ? nB : cB + (size_t)(t + 2) * kstep;
;             const char* a3 = a2 + kstep; const char* b3 = b2 + kstep;
;             if (last && has_next) S.a_ready(nxt);
;             if constexpr (SP2) {
;             PG8_LDB(B0, 0, 0); PG8_LDB(B1, 0, 1); PG8_SCHED; PG8_LDA(At, 0, 0); PG8_STAGE(PG8_SA(1, 0), a1, voffA); PG8_STAGE(PG8_SA(1, 1), a1 + hstep, voffA);
;             PG8_WAIT_V(8); PG8_WAIT_L(0); PG8_BAR; PG8_MMA(0, 0, At, B0); PG8_MMA(0, 1, At, B1); PG8_BAR; PG8_SCHED;
;     ...
; #pragma unroll
;         for (int a = 0; a < 2; ++a)
; #pragma unroll
;             for (int b = 0; b < 2; ++b)
; #pragma unroll
;                 for (int m = 0; m < 4; ++m)
; #pragma unroll
;                     for (int n = 0; n < 2; ++n) acc[a][b][m][n] = (f32x4){0.f, 0.f, 0.f, 0.f};
;         cur = nxt; cA = nA; cB = nB; ++ui;
.LBB0_211:
	s_ashr_i32 s89, s88, 31
	s_lshl_b64 s[4:5], s[88:89], 20
	s_add_u32 s4, s22, s4
	s_addc_u32 s5, s75, s5
	s_and_b64 s[6:7], s[38:39], exec
	s_cselect_b32 s89, s5, s9
	s_cselect_b32 vcc_lo, s4, s8
	s_ashr_i32 s73, s72, 31
	s_lshl_b64 s[6:7], s[72:73], 20
	s_add_u32 s6, s68, s6
	s_addc_u32 s7, s69, s7
	s_and_b64 s[16:17], s[38:39], exec
	s_cselect_b32 s70, s7, s11
	s_cselect_b32 s71, s6, s10
	s_add_u32 s73, s10, 0x100
	v_mov_b32_e32 v0, 0
	s_addc_u32 vcc_hi, s11, 0
	s_mov_b32 s52, -2
	s_mov_b64 s[10:11], 0
	v_mov_b32_e32 v1, v0
	v_mov_b32_e32 v2, v0
	v_mov_b32_e32 v3, v0
	v_mov_b32_e32 v4, v0
	v_mov_b32_e32 v5, v0
	v_mov_b32_e32 v6, v0
	v_mov_b32_e32 v7, v0
	v_mov_b32_e32 v16, v0
	v_mov_b32_e32 v17, v0
	v_mov_b32_e32 v18, v0
	v_mov_b32_e32 v19, v0
	v_mov_b32_e32 v20, v0
	v_mov_b32_e32 v21, v0
	v_mov_b32_e32 v22, v0
	v_mov_b32_e32 v23, v0
	v_mov_b32_e32 v32, v0
	v_mov_b32_e32 v33, v0
	v_mov_b32_e32 v34, v0
	v_mov_b32_e32 v35, v0
	v_mov_b32_e32 v36, v0
	v_mov_b32_e32 v37, v0
	v_mov_b32_e32 v38, v0
	v_mov_b32_e32 v39, v0
	v_mov_b32_e32 v48, v0
	v_mov_b32_e32 v49, v0
	v_mov_b32_e32 v50, v0
	v_mov_b32_e32 v51, v0
	v_mov_b32_e32 v52, v0
	v_mov_b32_e32 v53, v0
	v_mov_b32_e32 v54, v0
	v_mov_b32_e32 v55, v0
	v_mov_b32_e32 v8, v0
	v_mov_b32_e32 v9, v0
	v_mov_b32_e32 v10, v0
	v_mov_b32_e32 v11, v0
	v_mov_b32_e32 v12, v0
	v_mov_b32_e32 v13, v0
	v_mov_b32_e32 v14, v0
	v_mov_b32_e32 v15, v0
	v_mov_b32_e32 v24, v0
	v_mov_b32_e32 v25, v0
	v_mov_b32_e32 v26, v0
	v_mov_b32_e32 v27, v0
	v_mov_b32_e32 v28, v0
	v_mov_b32_e32 v29, v0
	v_mov_b32_e32 v30, v0
	v_mov_b32_e32 v31, v0
	v_mov_b32_e32 v40, v0
	v_mov_b32_e32 v41, v0
	v_mov_b32_e32 v42, v0
	v_mov_b32_e32 v43, v0
	v_mov_b32_e32 v44, v0
	v_mov_b32_e32 v45, v0
	v_mov_b32_e32 v46, v0
	v_mov_b32_e32 v47, v0
	v_mov_b32_e32 v56, v0
	v_mov_b32_e32 v57, v0
	v_mov_b32_e32 v58, v0
	v_mov_b32_e32 v59, v0
	v_mov_b32_e32 v60, v0
	v_mov_b32_e32 v61, v0
	v_mov_b32_e32 v62, v0
	v_mov_b32_e32 v63, v0
	v_mov_b32_e32 v64, v0
	v_mov_b32_e32 v65, v0
	v_mov_b32_e32 v66, v0
	v_mov_b32_e32 v67, v0
	v_mov_b32_e32 v68, v0
	v_mov_b32_e32 v69, v0
	v_mov_b32_e32 v70, v0
	v_mov_b32_e32 v71, v0
	v_mov_b32_e32 v80, v0
	v_mov_b32_e32 v81, v0
	v_mov_b32_e32 v82, v0
	v_mov_b32_e32 v83, v0
	v_mov_b32_e32 v84, v0
	v_mov_b32_e32 v85, v0
	v_mov_b32_e32 v86, v0
	v_mov_b32_e32 v87, v0
	v_mov_b32_e32 v96, v0
	v_mov_b32_e32 v97, v0
	v_mov_b32_e32 v98, v0
	v_mov_b32_e32 v99, v0
	v_mov_b32_e32 v100, v0
	v_mov_b32_e32 v101, v0
	v_mov_b32_e32 v102, v0
	v_mov_b32_e32 v103, v0
	v_mov_b32_e32 v112, v0
	v_mov_b32_e32 v113, v0
	v_mov_b32_e32 v114, v0
	v_mov_b32_e32 v115, v0
	v_mov_b32_e32 v116, v0
	v_mov_b32_e32 v117, v0
	v_mov_b32_e32 v118, v0
	v_mov_b32_e32 v119, v0
	v_mov_b32_e32 v72, v0
	v_mov_b32_e32 v73, v0
	v_mov_b32_e32 v74, v0
	v_mov_b32_e32 v75, v0
	v_mov_b32_e32 v76, v0
	v_mov_b32_e32 v77, v0
	v_mov_b32_e32 v78, v0
	v_mov_b32_e32 v79, v0
	v_mov_b32_e32 v88, v0
	v_mov_b32_e32 v89, v0
	v_mov_b32_e32 v90, v0
	v_mov_b32_e32 v91, v0
	v_mov_b32_e32 v92, v0
	v_mov_b32_e32 v93, v0
	v_mov_b32_e32 v94, v0
	v_mov_b32_e32 v95, v0
	v_mov_b32_e32 v104, v0
	v_mov_b32_e32 v105, v0
	v_mov_b32_e32 v106, v0
	v_mov_b32_e32 v107, v0
	v_mov_b32_e32 v108, v0
	v_mov_b32_e32 v109, v0
	v_mov_b32_e32 v110, v0
	v_mov_b32_e32 v111, v0
	v_mov_b32_e32 v120, v0
	v_mov_b32_e32 v121, v0
	v_mov_b32_e32 v122, v0
	v_mov_b32_e32 v123, v0
	v_mov_b32_e32 v124, v0
	v_mov_b32_e32 v125, v0
	v_mov_b32_e32 v126, v0
	v_mov_b32_e32 v127, v0
	v_lshl_add_u64 v[138:139], s[8:9], 0, v[134:135]
	v_lshl_add_u64 v[140:141], s[8:9], 0, v[136:137]
	s_cmp_eq_u64 s[46:47], 0
	s_cbranch_scc1 .Lg1_np
	s_setprio 1
.Lg1_np:
.LBB0_212:
	s_add_u32 s16, s8, s10
	s_addc_u32 s17, s9, s11
	s_add_u32 s44, s16, 0x100
	s_addc_u32 s45, s17, 0
	s_add_u32 s16, s73, s10
	s_addc_u32 s17, vcc_hi, s11
	s_add_i32 s53, 0, 0x10000
	s_cmpk_eq_i32 s10, 0xf00
	s_cselect_b32 s17, s70, s17
	s_cselect_b32 s16, s71, s16
	s_cselect_b32 s45, s89, s45
	s_cselect_b32 s44, vcc_lo, s44
	s_add_i32 s92, 0, 0x14000
	v_add_u32_e32 v158, s53, v147
	v_add_u32_e32 v174, s92, v147
	ds_read_b128 v[142:145], v158
	ds_read_b128 v[150:153], v158 offset:1024
	ds_read_b128 v[154:157], v158 offset:2048
	ds_read_b128 v[158:161], v158 offset:3072
	ds_read_b128 v[162:165], v174
	ds_read_b128 v[166:169], v174 offset:1024
	ds_read_b128 v[170:173], v174 offset:2048
	ds_read_b128 v[174:177], v174 offset:3072
	v_lshl_add_u64 v[202:203], v[138:139], 0, s[10:11]
	v_lshl_add_u64 v[206:207], v[202:203], 0, s[26:27]
	s_add_i32 m0, s97, 0x8000
	ds_read_b128 v[178:181], v149
	ds_read_b128 v[182:185], v149 offset:1024
	ds_read_b128 v[186:189], v149 offset:2048
	ds_read_b128 v[190:193], v149 offset:3072
	ds_read_b128 v[194:197], v149 offset:4096
	ds_read_b128 v[198:201], v149 offset:5120
	ds_read_b128 v[218:221], v149 offset:6144
	ds_read_b128 v[232:235], v149 offset:7168
	global_load_lds_dwordx4 v[206:207], off
	v_lshl_add_u64 v[206:207], v[140:141], 0, s[10:11]
	v_lshl_add_u64 v[208:209], v[206:207], 0, s[26:27]
	s_add_i32 m0, s97, 0xa000
	v_lshl_add_u64 v[202:203], v[202:203], 0, s[28:29]
	global_load_lds_dwordx4 v[208:209], off
	s_add_i32 m0, s97, 0xc000
	s_nop 0
	global_load_lds_dwordx4 v[202:203], off
	v_lshl_add_u64 v[202:203], v[206:207], 0, s[28:29]
	s_add_i32 m0, s97, 0xe000
	s_nop 0
	global_load_lds_dwordx4 v[202:203], off
	s_waitcnt vmcnt(8)
	s_waitcnt lgkmcnt(0)
	s_barrier
; #define PG8_STAGE(bufoff, gbase, voff) do { _Pragma("unroll") for (int _i = 0; _i < 2; ++_i) \
;         __builtin_amdgcn_global_load_lds((const unsigned*)((const char*)(gbase) + (voff)[_i]), (PG8_LAS unsigned*)(lds + (bufoff) + ldsw + _i * 8192), 16, 0, 0); } while (0)
; #define PG8_LDA(dst, b, h) do { _Pragma("unroll") for (int m = 0; m < 4; ++m) _Pragma("unroll") for (int k = 0; k < 2; ++k) dst[m][k] = *(const PG8_LAS bf16x8*)(lds + PG8_SA(b, h) + aoff + m * 2048 + k * 1024); } while (0)
; #define PG8_MMA(ai, bj, At, Bt) do { __builtin_amdgcn_s_setprio(1); _Pragma("unroll") for (int m = 0; m < 4; ++m) _Pragma("unroll") for (int n = 0; n < 2; ++n) _Pragma("unroll") for (int k = 0; k < 2; ++k) \
;         acc[ai][bj][m][n] = __builtin_amdgcn_mfma_f32_16x16x32_bf16(Bt[n][k], At[m][k], acc[ai][bj][m][n], 0, 0, 0); __builtin_amdgcn_s_setprio(0); } while (0)
; #define PG8_WAIT_V(n) asm volatile("s_waitcnt vmcnt(" #n ")" ::: "memory")
; #define PG8_WAIT_L(n) asm volatile("s_waitcnt lgkmcnt(" #n ")" ::: "memory")
; #define PG8_BAR __builtin_amdgcn_s_barrier()
; #define PG8_SCHED __builtin_amdgcn_sched_barrier(0)
; template <class Epi, class Sched, bool ALIGN_EPI = false, bool SP2 = false>
; __device__ __forceinline__ void gemm_phase(PG8_LAS unsigned char* lds, const Gemm g, const Sched& S, const Epi& E) {
;     ...
;             PG8_WAIT_V(8); PG8_WAIT_L(0); PG8_BAR; PG8_MMA(0, 0, At, B0); PG8_MMA(0, 1, At, B1); PG8_BAR; PG8_SCHED;
;             PG8_LDA(At, 0, 1); PG8_STAGE(PG8_SB(0, 0), b2, voffB); PG8_STAGE(PG8_SB(0, 1), b2 + hstep, voffB);
;             PG8_WAIT_V(6); PG8_WAIT_L(0); PG8_BAR; PG8_MMA(1, 0, At, B0); PG8_MMA(1, 1, At, B1); PG8_BAR; PG8_SCHED;
	v_mfma_f32_16x16x32_bf16 v[124:127], v[142:145], v[178:181], v[124:127]
	v_mfma_f32_16x16x32_bf16 v[120:123], v[154:157], v[178:181], v[120:123]
	v_mfma_f32_16x16x32_bf16 v[108:111], v[142:145], v[186:189], v[108:111]
	v_mfma_f32_16x16x32_bf16 v[104:107], v[154:157], v[186:189], v[104:107]
	v_mfma_f32_16x16x32_bf16 v[92:95], v[142:145], v[194:197], v[92:95]
	v_mfma_f32_16x16x32_bf16 v[88:91], v[154:157], v[194:197], v[88:91]
	v_mfma_f32_16x16x32_bf16 v[76:79], v[142:145], v[218:221], v[76:79]
	v_mfma_f32_16x16x32_bf16 v[72:75], v[154:157], v[218:221], v[72:75]
	v_mfma_f32_16x16x32_bf16 v[124:127], v[150:153], v[182:185], v[124:127]
	v_mfma_f32_16x16x32_bf16 v[120:123], v[158:161], v[182:185], v[120:123]
	v_mfma_f32_16x16x32_bf16 v[108:111], v[150:153], v[190:193], v[108:111]
	v_mfma_f32_16x16x32_bf16 v[104:107], v[158:161], v[190:193], v[104:107]
	v_mfma_f32_16x16x32_bf16 v[92:95], v[150:153], v[198:201], v[92:95]
	v_mfma_f32_16x16x32_bf16 v[88:91], v[158:161], v[198:201], v[88:91]
	v_mfma_f32_16x16x32_bf16 v[76:79], v[150:153], v[232:235], v[76:79]
	v_mfma_f32_16x16x32_bf16 v[72:75], v[158:161], v[232:235], v[72:75]
	v_mfma_f32_16x16x32_bf16 v[116:119], v[162:165], v[178:181], v[116:119]
	v_mfma_f32_16x16x32_bf16 v[112:115], v[170:173], v[178:181], v[112:115]
	v_mfma_f32_16x16x32_bf16 v[100:103], v[162:165], v[186:189], v[100:103]
	v_mfma_f32_16x16x32_bf16 v[96:99], v[170:173], v[186:189], v[96:99]
	v_mfma_f32_16x16x32_bf16 v[84:87], v[162:165], v[194:197], v[84:87]
	v_mfma_f32_16x16x32_bf16 v[80:83], v[170:173], v[194:197], v[80:83]
	v_mfma_f32_16x16x32_bf16 v[68:71], v[162:165], v[218:221], v[68:71]
	v_mfma_f32_16x16x32_bf16 v[64:67], v[170:173], v[218:221], v[64:67]
	v_mfma_f32_16x16x32_bf16 v[116:119], v[166:169], v[182:185], v[116:119]
	v_mfma_f32_16x16x32_bf16 v[112:115], v[174:177], v[182:185], v[112:115]
	v_mfma_f32_16x16x32_bf16 v[100:103], v[166:169], v[190:193], v[100:103]
	v_mfma_f32_16x16x32_bf16 v[96:99], v[174:177], v[190:193], v[96:99]
	v_mfma_f32_16x16x32_bf16 v[84:87], v[166:169], v[198:201], v[84:87]
	v_mfma_f32_16x16x32_bf16 v[80:83], v[174:177], v[198:201], v[80:83]
	v_mfma_f32_16x16x32_bf16 v[68:71], v[166:169], v[232:235], v[68:71]
	v_mfma_f32_16x16x32_bf16 v[64:67], v[174:177], v[232:235], v[64:67]
	s_barrier
	s_add_i32 s53, s53, s23
	v_lshl_add_u64 v[202:203], s[16:17], 0, v[204:205]
	s_mov_b32 m0, s53
	ds_read_b128 v[178:181], v149 offset:16384
	ds_read_b128 v[182:185], v149 offset:17408
	ds_read_b128 v[186:189], v149 offset:18432
	ds_read_b128 v[190:193], v149 offset:19456
	ds_read_b128 v[194:197], v149 offset:20480
	ds_read_b128 v[198:201], v149 offset:21504
	ds_read_b128 v[218:221], v149 offset:22528
	ds_read_b128 v[232:235], v149 offset:23552
	global_load_lds_dwordx4 v[202:203], off
	s_add_i32 m0, s53, 0x2000
	s_add_u32 s78, s16, 0x80000
	v_lshl_add_u64 v[206:207], s[16:17], 0, v[128:129]
	s_addc_u32 s79, s17, 0
	s_add_i32 s53, s92, s23
	global_load_lds_dwordx4 v[206:207], off
	v_lshl_add_u64 v[208:209], s[78:79], 0, v[204:205]
	s_mov_b32 m0, s53
	s_nop 0
	global_load_lds_dwordx4 v[208:209], off
	v_lshl_add_u64 v[208:209], s[78:79], 0, v[128:129]
	s_add_i32 m0, s53, 0x2000
	s_nop 0
	global_load_lds_dwordx4 v[208:209], off
	s_waitcnt vmcnt(6)
	s_waitcnt lgkmcnt(0)
	s_barrier
	v_mfma_f32_16x16x32_bf16 v[60:63], v[142:145], v[178:181], v[60:63]
	v_mfma_f32_16x16x32_bf16 v[56:59], v[154:157], v[178:181], v[56:59]
	v_mfma_f32_16x16x32_bf16 v[44:47], v[142:145], v[186:189], v[44:47]
	v_mfma_f32_16x16x32_bf16 v[40:43], v[154:157], v[186:189], v[40:43]
	v_mfma_f32_16x16x32_bf16 v[28:31], v[142:145], v[194:197], v[28:31]
	v_mfma_f32_16x16x32_bf16 v[24:27], v[154:157], v[194:197], v[24:27]
	v_mfma_f32_16x16x32_bf16 v[12:15], v[142:145], v[218:221], v[12:15]
	v_mfma_f32_16x16x32_bf16 v[8:11], v[154:157], v[218:221], v[8:11]
	v_mfma_f32_16x16x32_bf16 v[60:63], v[150:153], v[182:185], v[60:63]
	v_mfma_f32_16x16x32_bf16 v[56:59], v[158:161], v[182:185], v[56:59]
	v_mfma_f32_16x16x32_bf16 v[44:47], v[150:153], v[190:193], v[44:47]
	v_mfma_f32_16x16x32_bf16 v[40:43], v[158:161], v[190:193], v[40:43]
	v_mfma_f32_16x16x32_bf16 v[28:31], v[150:153], v[198:201], v[28:31]
	v_mfma_f32_16x16x32_bf16 v[24:27], v[158:161], v[198:201], v[24:27]
	v_mfma_f32_16x16x32_bf16 v[12:15], v[150:153], v[232:235], v[12:15]
	v_mfma_f32_16x16x32_bf16 v[8:11], v[158:161], v[232:235], v[8:11]
	v_mfma_f32_16x16x32_bf16 v[52:55], v[162:165], v[178:181], v[52:55]
	v_mfma_f32_16x16x32_bf16 v[48:51], v[170:173], v[178:181], v[48:51]
	v_mfma_f32_16x16x32_bf16 v[36:39], v[162:165], v[186:189], v[36:39]
	v_mfma_f32_16x16x32_bf16 v[32:35], v[170:173], v[186:189], v[32:35]
	v_mfma_f32_16x16x32_bf16 v[20:23], v[162:165], v[194:197], v[20:23]
	v_mfma_f32_16x16x32_bf16 v[16:19], v[170:173], v[194:197], v[16:19]
	v_mfma_f32_16x16x32_bf16 v[4:7], v[162:165], v[218:221], v[4:7]
	v_mfma_f32_16x16x32_bf16 v[0:3], v[170:173], v[218:221], v[0:3]
	v_mfma_f32_16x16x32_bf16 v[52:55], v[166:169], v[182:185], v[52:55]
	v_mfma_f32_16x16x32_bf16 v[48:51], v[174:177], v[182:185], v[48:51]
	v_mfma_f32_16x16x32_bf16 v[36:39], v[166:169], v[190:193], v[36:39]
	v_mfma_f32_16x16x32_bf16 v[32:35], v[174:177], v[190:193], v[32:35]
	v_mfma_f32_16x16x32_bf16 v[20:23], v[166:169], v[198:201], v[20:23]
	v_mfma_f32_16x16x32_bf16 v[16:19], v[174:177], v[198:201], v[16:19]
	v_mfma_f32_16x16x32_bf16 v[4:7], v[166:169], v[232:235], v[4:7]
	v_mfma_f32_16x16x32_bf16 v[0:3], v[174:177], v[232:235], v[0:3]
	s_barrier
; #define PG8_STAGE(bufoff, gbase, voff) do { _Pragma("unroll") for (int _i = 0; _i < 2; ++_i) \
;         __builtin_amdgcn_global_load_lds((const unsigned*)((const char*)(gbase) + (voff)[_i]), (PG8_LAS unsigned*)(lds + (bufoff) + ldsw + _i * 8192), 16, 0, 0); } while (0)
; #define PG8_LDA(dst, b, h) do { _Pragma("unroll") for (int m = 0; m < 4; ++m) _Pragma("unroll") for (int k = 0; k < 2; ++k) dst[m][k] = *(const PG8_LAS bf16x8*)(lds + PG8_SA(b, h) + aoff + m * 2048 + k * 1024); } while (0)
; #define PG8_LDB(dst, b, h) do { _Pragma("unroll") for (int n = 0; n < 2; ++n) _Pragma("unroll") for (int k = 0; k < 2; ++k) dst[n][k] = *(const PG8_LAS bf16x8*)(lds + PG8_SB(b, h) + boff + n * 2048 + k * 1024); } while (0)
; #define PG8_MMA(ai, bj, At, Bt) do { __builtin_amdgcn_s_setprio(1); _Pragma("unroll") for (int m = 0; m < 4; ++m) _Pragma("unroll") for (int n = 0; n < 2; ++n) _Pragma("unroll") for (int k = 0; k < 2; ++k) \
;         acc[ai][bj][m][n] = __builtin_amdgcn_mfma_f32_16x16x32_bf16(Bt[n][k], At[m][k], acc[ai][bj][m][n], 0, 0, 0); __builtin_amdgcn_s_setprio(0); } while (0)
; #define PG8_WAIT_V(n) asm volatile("s_waitcnt vmcnt(" #n ")" ::: "memory")
; #define PG8_WAIT_L(n) asm volatile("s_waitcnt lgkmcnt(" #n ")" ::: "memory")
; #define PG8_BAR __builtin_amdgcn_s_barrier()
; #define PG8_SCHED __builtin_amdgcn_sched_barrier(0)
; template <class Epi, class Sched, bool ALIGN_EPI = false, bool SP2 = false>
; __device__ __forceinline__ void gemm_phase(PG8_LAS unsigned char* lds, const Gemm g, const Sched& S, const Epi& E) {
;     ...
;             PG8_LDB(B0, 1, 0); PG8_LDB(B1, 1, 1); PG8_SCHED; PG8_LDA(At, 1, 0); PG8_STAGE(PG8_SA(0, 0), a2, voffA); PG8_STAGE(PG8_SA(0, 1), a2 + hstep, voffA);
;             PG8_WAIT_V(8); PG8_WAIT_L(0); PG8_BAR; PG8_MMA(0, 0, At, B0); PG8_MMA(0, 1, At, B1); PG8_BAR; PG8_SCHED;
;             PG8_LDA(At, 1, 1); PG8_STAGE(PG8_SB(1, 0), b3, voffB); PG8_STAGE(PG8_SB(1, 1), b3 + hstep, voffB); (void)a3;
;             PG8_WAIT_V(6); PG8_WAIT_L(0); PG8_BAR; PG8_MMA(1, 0, At, B0); PG8_MMA(1, 1, At, B1); PG8_BAR; PG8_SCHED;
;     ...
;         if constexpr (ALIGN_EPI) { if (wr == 0) PG8_BAR; }
	s_add_i32 s53, 0, 0x18000
	s_add_i32 s78, 0, 0x1c000
	v_add_u32_e32 v158, s53, v147
	v_add_u32_e32 v174, s78, v147
	ds_read_b128 v[142:145], v158
	ds_read_b128 v[150:153], v158 offset:1024
	ds_read_b128 v[154:157], v158 offset:2048
	ds_read_b128 v[158:161], v158 offset:3072
	ds_read_b128 v[162:165], v174
	ds_read_b128 v[166:169], v174 offset:1024
	ds_read_b128 v[170:173], v174 offset:2048
	ds_read_b128 v[174:177], v174 offset:3072
	s_mov_b32 m0, s97
	v_lshl_add_u64 v[208:209], s[44:45], 0, v[132:133]
	ds_read_b128 v[178:181], v149 offset:32768
	ds_read_b128 v[182:185], v149 offset:33792
	ds_read_b128 v[186:189], v149 offset:34816
	ds_read_b128 v[190:193], v149 offset:35840
	ds_read_b128 v[194:197], v149 offset:36864
	ds_read_b128 v[198:201], v149 offset:37888
	ds_read_b128 v[218:221], v149 offset:38912
	ds_read_b128 v[232:235], v149 offset:39936
	global_load_lds_dwordx4 v[208:209], off
	v_lshl_add_u64 v[208:209], s[44:45], 0, v[130:131]
	s_add_u32 s44, s44, 0x80000
	s_mov_b32 m0, s20
	s_addc_u32 s45, s45, 0
	global_load_lds_dwordx4 v[208:209], off
	v_lshl_add_u64 v[208:209], s[44:45], 0, v[132:133]
	s_mov_b32 m0, s21
	s_nop 0
	global_load_lds_dwordx4 v[208:209], off
	v_lshl_add_u64 v[208:209], s[44:45], 0, v[130:131]
	s_mov_b32 m0, s57
	s_nop 0
	global_load_lds_dwordx4 v[208:209], off
	s_waitcnt vmcnt(8)
	s_waitcnt lgkmcnt(0)
	s_barrier
	v_mfma_f32_16x16x32_bf16 v[124:127], v[142:145], v[178:181], v[124:127]
	v_mfma_f32_16x16x32_bf16 v[120:123], v[154:157], v[178:181], v[120:123]
	v_mfma_f32_16x16x32_bf16 v[108:111], v[142:145], v[186:189], v[108:111]
	v_mfma_f32_16x16x32_bf16 v[104:107], v[154:157], v[186:189], v[104:107]
	v_mfma_f32_16x16x32_bf16 v[92:95], v[142:145], v[194:197], v[92:95]
	v_mfma_f32_16x16x32_bf16 v[88:91], v[154:157], v[194:197], v[88:91]
	v_mfma_f32_16x16x32_bf16 v[76:79], v[142:145], v[218:221], v[76:79]
	v_mfma_f32_16x16x32_bf16 v[72:75], v[154:157], v[218:221], v[72:75]
	v_mfma_f32_16x16x32_bf16 v[124:127], v[150:153], v[182:185], v[124:127]
	v_mfma_f32_16x16x32_bf16 v[120:123], v[158:161], v[182:185], v[120:123]
	v_mfma_f32_16x16x32_bf16 v[108:111], v[150:153], v[190:193], v[108:111]
	v_mfma_f32_16x16x32_bf16 v[104:107], v[158:161], v[190:193], v[104:107]
	v_mfma_f32_16x16x32_bf16 v[92:95], v[150:153], v[198:201], v[92:95]
	v_mfma_f32_16x16x32_bf16 v[88:91], v[158:161], v[198:201], v[88:91]
	v_mfma_f32_16x16x32_bf16 v[76:79], v[150:153], v[232:235], v[76:79]
	v_mfma_f32_16x16x32_bf16 v[72:75], v[158:161], v[232:235], v[72:75]
	v_mfma_f32_16x16x32_bf16 v[116:119], v[162:165], v[178:181], v[116:119]
	v_mfma_f32_16x16x32_bf16 v[112:115], v[170:173], v[178:181], v[112:115]
	v_mfma_f32_16x16x32_bf16 v[100:103], v[162:165], v[186:189], v[100:103]
	v_mfma_f32_16x16x32_bf16 v[96:99], v[170:173], v[186:189], v[96:99]
	v_mfma_f32_16x16x32_bf16 v[84:87], v[162:165], v[194:197], v[84:87]
	v_mfma_f32_16x16x32_bf16 v[80:83], v[170:173], v[194:197], v[80:83]
	v_mfma_f32_16x16x32_bf16 v[68:71], v[162:165], v[218:221], v[68:71]
	v_mfma_f32_16x16x32_bf16 v[64:67], v[170:173], v[218:221], v[64:67]
	v_mfma_f32_16x16x32_bf16 v[116:119], v[166:169], v[182:185], v[116:119]
	v_mfma_f32_16x16x32_bf16 v[112:115], v[174:177], v[182:185], v[112:115]
	v_mfma_f32_16x16x32_bf16 v[100:103], v[166:169], v[190:193], v[100:103]
	v_mfma_f32_16x16x32_bf16 v[96:99], v[174:177], v[190:193], v[96:99]
	v_mfma_f32_16x16x32_bf16 v[84:87], v[166:169], v[198:201], v[84:87]
	v_mfma_f32_16x16x32_bf16 v[80:83], v[174:177], v[198:201], v[80:83]
	v_mfma_f32_16x16x32_bf16 v[68:71], v[166:169], v[232:235], v[68:71]
	v_mfma_f32_16x16x32_bf16 v[64:67], v[174:177], v[232:235], v[64:67]
	s_barrier
	s_add_i32 s44, s53, s23
	v_lshl_add_u64 v[202:203], v[202:203], 0, s[26:27]
	s_mov_b32 m0, s44
	ds_read_b128 v[178:181], v149 offset:49152
	ds_read_b128 v[182:185], v149 offset:50176
	ds_read_b128 v[186:189], v149 offset:51200
	ds_read_b128 v[190:193], v149 offset:52224
	ds_read_b128 v[194:197], v149 offset:53248
	ds_read_b128 v[198:201], v149 offset:54272
	ds_read_b128 v[218:221], v149 offset:55296
	ds_read_b128 v[232:235], v149 offset:56320
	global_load_lds_dwordx4 v[202:203], off
	s_add_i32 m0, s44, 0x2000
	s_add_u32 s16, s16, 0x80080
	v_lshl_add_u64 v[202:203], v[206:207], 0, s[26:27]
	s_addc_u32 s17, s17, 0
	s_add_i32 s44, s78, s23
	global_load_lds_dwordx4 v[202:203], off
	v_lshl_add_u64 v[202:203], s[16:17], 0, v[204:205]
	s_mov_b32 m0, s44
	s_nop 0
	global_load_lds_dwordx4 v[202:203], off
	v_lshl_add_u64 v[202:203], s[16:17], 0, v[128:129]
	s_add_i32 m0, s44, 0x2000
	s_nop 0
	global_load_lds_dwordx4 v[202:203], off
	s_waitcnt vmcnt(6)
	s_waitcnt lgkmcnt(0)
	s_barrier
	v_mfma_f32_16x16x32_bf16 v[60:63], v[142:145], v[178:181], v[60:63]
	v_mfma_f32_16x16x32_bf16 v[56:59], v[154:157], v[178:181], v[56:59]
	v_mfma_f32_16x16x32_bf16 v[44:47], v[142:145], v[186:189], v[44:47]
	v_mfma_f32_16x16x32_bf16 v[40:43], v[154:157], v[186:189], v[40:43]
	v_mfma_f32_16x16x32_bf16 v[28:31], v[142:145], v[194:197], v[28:31]
	v_mfma_f32_16x16x32_bf16 v[24:27], v[154:157], v[194:197], v[24:27]
	v_mfma_f32_16x16x32_bf16 v[12:15], v[142:145], v[218:221], v[12:15]
	v_mfma_f32_16x16x32_bf16 v[8:11], v[154:157], v[218:221], v[8:11]
	v_mfma_f32_16x16x32_bf16 v[60:63], v[150:153], v[182:185], v[60:63]
	v_mfma_f32_16x16x32_bf16 v[56:59], v[158:161], v[182:185], v[56:59]
	v_mfma_f32_16x16x32_bf16 v[44:47], v[150:153], v[190:193], v[44:47]
	v_mfma_f32_16x16x32_bf16 v[40:43], v[158:161], v[190:193], v[40:43]
	v_mfma_f32_16x16x32_bf16 v[28:31], v[150:153], v[198:201], v[28:31]
	v_mfma_f32_16x16x32_bf16 v[24:27], v[158:161], v[198:201], v[24:27]
	v_mfma_f32_16x16x32_bf16 v[12:15], v[150:153], v[232:235], v[12:15]
	v_mfma_f32_16x16x32_bf16 v[8:11], v[158:161], v[232:235], v[8:11]
	v_mfma_f32_16x16x32_bf16 v[52:55], v[162:165], v[178:181], v[52:55]
	v_mfma_f32_16x16x32_bf16 v[48:51], v[170:173], v[178:181], v[48:51]
	v_mfma_f32_16x16x32_bf16 v[36:39], v[162:165], v[186:189], v[36:39]
	v_mfma_f32_16x16x32_bf16 v[32:35], v[170:173], v[186:189], v[32:35]
	v_mfma_f32_16x16x32_bf16 v[20:23], v[162:165], v[194:197], v[20:23]
	v_mfma_f32_16x16x32_bf16 v[16:19], v[170:173], v[194:197], v[16:19]
	v_mfma_f32_16x16x32_bf16 v[4:7], v[162:165], v[218:221], v[4:7]
	v_mfma_f32_16x16x32_bf16 v[0:3], v[170:173], v[218:221], v[0:3]
	v_mfma_f32_16x16x32_bf16 v[52:55], v[166:169], v[182:185], v[52:55]
	v_mfma_f32_16x16x32_bf16 v[48:51], v[174:177], v[182:185], v[48:51]
	v_mfma_f32_16x16x32_bf16 v[36:39], v[166:169], v[190:193], v[36:39]
	v_mfma_f32_16x16x32_bf16 v[32:35], v[174:177], v[190:193], v[32:35]
	v_mfma_f32_16x16x32_bf16 v[20:23], v[166:169], v[198:201], v[20:23]
	v_mfma_f32_16x16x32_bf16 v[16:19], v[174:177], v[198:201], v[16:19]
	v_mfma_f32_16x16x32_bf16 v[4:7], v[166:169], v[232:235], v[4:7]
	v_mfma_f32_16x16x32_bf16 v[0:3], v[174:177], v[232:235], v[0:3]
	s_barrier
	s_add_i32 s52, s52, 2
	s_add_u32 s10, s10, 0x100
	s_addc_u32 s11, s11, 0
	s_cmp_gt_u32 s52, 29
	s_cbranch_scc0 .LBB0_212
	s_setprio 0
	s_and_b64 vcc, exec, s[76:77]
	s_cbranch_vccz .LBB0_215
	s_barrier

; #define PG8_STAGE(bufoff, gbase, voff) do { _Pragma("unroll") for (int _i = 0; _i < 2; ++_i) \
;         __builtin_amdgcn_global_load_lds((const unsigned*)((const char*)(gbase) + (voff)[_i]), (PG8_LAS unsigned*)(lds + (bufoff) + ldsw + _i * 8192), 16, 0, 0); } while (0)
; #define PG8_LDA(dst, b, h) do { _Pragma("unroll") for (int m = 0; m < 4; ++m) _Pragma("unroll") for (int k = 0; k < 2; ++k) dst[m][k] = *(const PG8_LAS bf16x8*)(lds + PG8_SA(b, h) + aoff + m * 2048 + k * 1024); } while (0)
; #define PG8_LDB(dst, b, h) do { _Pragma("unroll") for (int n = 0; n < 2; ++n) _Pragma("unroll") for (int k = 0; k < 2; ++k) dst[n][k] = *(const PG8_LAS bf16x8*)(lds + PG8_SB(b, h) + boff + n * 2048 + k * 1024); } while (0)
; #define PG8_WAIT_V(n) asm volatile("s_waitcnt vmcnt(" #n ")" ::: "memory")
; #define PG8_WAIT_L(n) asm volatile("s_waitcnt lgkmcnt(" #n ")" ::: "memory")
; #define PG8_BAR __builtin_amdgcn_s_barrier()
; template <class Epi, class Sched, bool ALIGN_EPI = false, bool SP2 = false>
; __device__ __forceinline__ void gemm_phase(PG8_LAS unsigned char* lds, const Gemm g, const Sched& S, const Epi& E) {
;     ...
;         const bool has_next = S.next(ui + 1, nxt);
;         const char* nA = has_next ? (const char*)g.A + (size_t)nxt.pm * tstep : cA; const char* nB = has_next ? (const char*)g.Bt + (size_t)nxt.pn * tstep : cB;
;         for (int t = 0; t < nt; t += 2) {
;             const bool last = (t == nt - 2);
;             const char* a1 = cA + (size_t)(t + 1) * kstep;
;             const char* a2 = last ? nA : cA + (size_t)(t + 2) * kstep; const char* b2 = last ? nB : cB + (size_t)(t + 2) * kstep;
;             const char* a3 = a2 + kstep; const char* b3 = b2 + kstep;
;             if (last && has_next) S.a_ready(nxt);
;             if constexpr (SP2) {
;             PG8_LDB(B0, 0, 0); PG8_LDB(B1, 0, 1); PG8_SCHED; PG8_LDA(At, 0, 0); PG8_STAGE(PG8_SA(1, 0), a1, voffA); PG8_STAGE(PG8_SA(1, 1), a1 + hstep, voffA);
;             PG8_WAIT_V(8); PG8_WAIT_L(0); PG8_BAR; PG8_MMA(0, 0, At, B0); PG8_MMA(0, 1, At, B1); PG8_BAR; PG8_SCHED;
;     ...
; #pragma unroll
;         for (int a = 0; a < 2; ++a)
; #pragma unroll
;             for (int b = 0; b < 2; ++b)
; #pragma unroll
;                 for (int m = 0; m < 4; ++m)
; #pragma unroll
;                     for (int n = 0; n < 2; ++n) acc[a][b][m][n] = (f32x4){0.f, 0.f, 0.f, 0.f};
;         cur = nxt; cA = nA; cB = nB; ++ui;
.LBB0_231:
	s_ashr_i32 s47, s46, 31
	s_lshl_b64 s[52:53], s[46:47], 20
	s_add_u32 s72, s20, s52
	s_addc_u32 s73, s21, s53
	s_and_b64 s[52:53], s[38:39], exec
	s_cselect_b32 s47, s73, s17
	s_cselect_b32 s68, s72, s16
	s_ashr_i32 s11, s10, 31
	s_lshl_b64 s[52:53], s[10:11], 20
	s_add_u32 s76, s22, s52
	s_addc_u32 s77, s75, s53
	s_and_b64 s[52:53], s[38:39], exec
	s_cselect_b32 s11, s77, s45
	s_cselect_b32 s69, s76, s44
	s_add_u32 s70, s44, 0x100
	v_mov_b32_e32 v0, 0
	s_addc_u32 s71, s45, 0
	v_lshl_add_u64 v[96:97], s[16:17], 0, v[150:151]
	v_lshl_add_u64 v[98:99], s[16:17], 0, v[152:153]
	s_mov_b32 s52, -2
	s_mov_b64 s[88:89], 0
	v_mov_b32_e32 v1, v0
	v_mov_b32_e32 v2, v0
	v_mov_b32_e32 v3, v0
	v_mov_b32_e32 v4, v0
	v_mov_b32_e32 v5, v0
	v_mov_b32_e32 v6, v0
	v_mov_b32_e32 v7, v0
	v_mov_b32_e32 v12, v0
	v_mov_b32_e32 v13, v0
	v_mov_b32_e32 v14, v0
	v_mov_b32_e32 v15, v0
	v_mov_b32_e32 v20, v0
	v_mov_b32_e32 v21, v0
	v_mov_b32_e32 v22, v0
	v_mov_b32_e32 v23, v0
	v_mov_b32_e32 v28, v0
	v_mov_b32_e32 v29, v0
	v_mov_b32_e32 v30, v0
	v_mov_b32_e32 v31, v0
	v_mov_b32_e32 v36, v0
	v_mov_b32_e32 v37, v0
	v_mov_b32_e32 v38, v0
	v_mov_b32_e32 v39, v0
	v_mov_b32_e32 v44, v0
	v_mov_b32_e32 v45, v0
	v_mov_b32_e32 v46, v0
	v_mov_b32_e32 v47, v0
	v_mov_b32_e32 v52, v0
	v_mov_b32_e32 v53, v0
	v_mov_b32_e32 v54, v0
	v_mov_b32_e32 v55, v0
	v_mov_b32_e32 v8, v0
	v_mov_b32_e32 v9, v0
	v_mov_b32_e32 v10, v0
	v_mov_b32_e32 v11, v0
	v_mov_b32_e32 v16, v0
	v_mov_b32_e32 v17, v0
	v_mov_b32_e32 v18, v0
	v_mov_b32_e32 v19, v0
	v_mov_b32_e32 v24, v0
	v_mov_b32_e32 v25, v0
	v_mov_b32_e32 v26, v0
	v_mov_b32_e32 v27, v0
	v_mov_b32_e32 v32, v0
	v_mov_b32_e32 v33, v0
	v_mov_b32_e32 v34, v0
	v_mov_b32_e32 v35, v0
	v_mov_b32_e32 v40, v0
	v_mov_b32_e32 v41, v0
	v_mov_b32_e32 v42, v0
	v_mov_b32_e32 v43, v0
	v_mov_b32_e32 v48, v0
	v_mov_b32_e32 v49, v0
	v_mov_b32_e32 v50, v0
	v_mov_b32_e32 v51, v0
	v_mov_b32_e32 v56, v0
	v_mov_b32_e32 v57, v0
	v_mov_b32_e32 v58, v0
	v_mov_b32_e32 v59, v0
	v_mov_b32_e32 v60, v0
	v_mov_b32_e32 v61, v0
	v_mov_b32_e32 v62, v0
	v_mov_b32_e32 v63, v0
	v_mov_b32_e32 v64, v0
	v_mov_b32_e32 v65, v0
	v_mov_b32_e32 v66, v0
	v_mov_b32_e32 v67, v0
	v_mov_b32_e32 v68, v0
	v_mov_b32_e32 v69, v0
	v_mov_b32_e32 v70, v0
	v_mov_b32_e32 v71, v0
	v_mov_b32_e32 v80, v0
	v_mov_b32_e32 v81, v0
	v_mov_b32_e32 v82, v0
	v_mov_b32_e32 v83, v0
	v_mov_b32_e32 v84, v0
	v_mov_b32_e32 v85, v0
	v_mov_b32_e32 v86, v0
	v_mov_b32_e32 v87, v0
	v_mov_b32_e32 v112, v0
	v_mov_b32_e32 v113, v0
	v_mov_b32_e32 v114, v0
	v_mov_b32_e32 v115, v0
	v_mov_b32_e32 v116, v0
	v_mov_b32_e32 v117, v0
	v_mov_b32_e32 v118, v0
	v_mov_b32_e32 v119, v0
	v_mov_b32_e32 v128, v0
	v_mov_b32_e32 v129, v0
	v_mov_b32_e32 v130, v0
	v_mov_b32_e32 v131, v0
	v_mov_b32_e32 v132, v0
	v_mov_b32_e32 v133, v0
	v_mov_b32_e32 v134, v0
	v_mov_b32_e32 v135, v0
	v_mov_b32_e32 v72, v0
	v_mov_b32_e32 v73, v0
	v_mov_b32_e32 v74, v0
	v_mov_b32_e32 v75, v0
	v_mov_b32_e32 v76, v0
	v_mov_b32_e32 v77, v0
	v_mov_b32_e32 v78, v0
	v_mov_b32_e32 v79, v0
	v_mov_b32_e32 v88, v0
	v_mov_b32_e32 v89, v0
	v_mov_b32_e32 v90, v0
	v_mov_b32_e32 v91, v0
	v_mov_b32_e32 v92, v0
	v_mov_b32_e32 v93, v0
	v_mov_b32_e32 v94, v0
	v_mov_b32_e32 v95, v0
	v_mov_b32_e32 v120, v0
	v_mov_b32_e32 v121, v0
	v_mov_b32_e32 v122, v0
	v_mov_b32_e32 v123, v0
	v_mov_b32_e32 v124, v0
	v_mov_b32_e32 v125, v0
	v_mov_b32_e32 v126, v0
	v_mov_b32_e32 v127, v0
	v_mov_b32_e32 v136, v0
	v_mov_b32_e32 v137, v0
	v_mov_b32_e32 v138, v0
	v_mov_b32_e32 v139, v0
	v_mov_b32_e32 v140, v0
	v_mov_b32_e32 v141, v0
	v_mov_b32_e32 v142, v0
	v_mov_b32_e32 v143, v0
	s_cmp_eq_u64 s[4:5], 0
	s_cbranch_scc1 .Lg2_np
	s_setprio 1
.Lg2_np:
.LBB0_232:
	s_add_u32 s44, s16, s88
	s_addc_u32 s45, s17, s89
	s_add_u32 s53, s44, 0x100
	s_addc_u32 s78, s45, 0
	s_add_u32 s44, s70, s88
	s_addc_u32 s45, s71, s89
	s_add_i32 s79, 0, 0x10000
	s_cmpk_eq_i32 s88, 0xf00
	s_cselect_b32 s45, s11, s45
	s_cselect_b32 s44, s69, s44
	s_cselect_b32 s95, s47, s78
	s_cselect_b32 s94, s68, s53
	s_add_i32 s53, 0, 0x14000
	v_add_u32_e32 v154, s79, v161
	v_add_u32_e32 v158, s53, v161
	ds_read_b128 v[100:103], v154
	ds_read_b128 v[104:107], v154 offset:1024
	ds_read_b128 v[108:111], v154 offset:2048
	ds_read_b128 v[154:157], v154 offset:3072
	ds_read_b128 v[164:167], v158
	ds_read_b128 v[168:171], v158 offset:1024
	ds_read_b128 v[172:175], v158 offset:2048
	ds_read_b128 v[176:179], v158 offset:3072
	v_lshl_add_u64 v[158:159], v[96:97], 0, s[88:89]
	v_lshl_add_u64 v[206:207], v[158:159], 0, s[26:27]
	s_add_i32 m0, s57, 0x8000
	ds_read_b128 v[180:183], v163
	ds_read_b128 v[184:187], v163 offset:1024
	ds_read_b128 v[188:191], v163 offset:2048
	ds_read_b128 v[192:195], v163 offset:3072
	ds_read_b128 v[196:199], v163 offset:4096
	ds_read_b128 v[200:203], v163 offset:5120
	ds_read_b128 v[218:221], v163 offset:6144
	ds_read_b128 v[232:235], v163 offset:7168
	global_load_lds_dwordx4 v[206:207], off
	v_lshl_add_u64 v[206:207], v[98:99], 0, s[88:89]
	v_lshl_add_u64 v[208:209], v[206:207], 0, s[26:27]
	s_add_i32 m0, s57, 0xa000
	v_lshl_add_u64 v[158:159], v[158:159], 0, s[28:29]
	global_load_lds_dwordx4 v[208:209], off
	s_add_i32 m0, s57, 0xc000
	s_nop 0
	global_load_lds_dwordx4 v[158:159], off
	v_lshl_add_u64 v[158:159], v[206:207], 0, s[28:29]
	s_add_i32 m0, s57, 0xe000
	s_nop 0
	global_load_lds_dwordx4 v[158:159], off
	s_waitcnt vmcnt(8)
	s_waitcnt lgkmcnt(0)
	s_barrier
; #define PG8_STAGE(bufoff, gbase, voff) do { _Pragma("unroll") for (int _i = 0; _i < 2; ++_i) \
;         __builtin_amdgcn_global_load_lds((const unsigned*)((const char*)(gbase) + (voff)[_i]), (PG8_LAS unsigned*)(lds + (bufoff) + ldsw + _i * 8192), 16, 0, 0); } while (0)
; #define PG8_LDA(dst, b, h) do { _Pragma("unroll") for (int m = 0; m < 4; ++m) _Pragma("unroll") for (int k = 0; k < 2; ++k) dst[m][k] = *(const PG8_LAS bf16x8*)(lds + PG8_SA(b, h) + aoff + m * 2048 + k * 1024); } while (0)
; #define PG8_MMA(ai, bj, At, Bt) do { __builtin_amdgcn_s_setprio(1); _Pragma("unroll") for (int m = 0; m < 4; ++m) _Pragma("unroll") for (int n = 0; n < 2; ++n) _Pragma("unroll") for (int k = 0; k < 2; ++k) \
;         acc[ai][bj][m][n] = __builtin_amdgcn_mfma_f32_16x16x32_bf16(Bt[n][k], At[m][k], acc[ai][bj][m][n], 0, 0, 0); __builtin_amdgcn_s_setprio(0); } while (0)
; #define PG8_WAIT_V(n) asm volatile("s_waitcnt vmcnt(" #n ")" ::: "memory")
; #define PG8_WAIT_L(n) asm volatile("s_waitcnt lgkmcnt(" #n ")" ::: "memory")
; #define PG8_BAR __builtin_amdgcn_s_barrier()
; #define PG8_SCHED __builtin_amdgcn_sched_barrier(0)
; template <class Epi, class Sched, bool ALIGN_EPI = false, bool SP2 = false>
; __device__ __forceinline__ void gemm_phase(PG8_LAS unsigned char* lds, const Gemm g, const Sched& S, const Epi& E) {
;     ...
;             PG8_WAIT_V(8); PG8_WAIT_L(0); PG8_BAR; PG8_MMA(0, 0, At, B0); PG8_MMA(0, 1, At, B1); PG8_BAR; PG8_SCHED;
;             PG8_LDA(At, 0, 1); PG8_STAGE(PG8_SB(0, 0), b2, voffB); PG8_STAGE(PG8_SB(0, 1), b2 + hstep, voffB);
;             PG8_WAIT_V(6); PG8_WAIT_L(0); PG8_BAR; PG8_MMA(1, 0, At, B0); PG8_MMA(1, 1, At, B1); PG8_BAR; PG8_SCHED;
	v_mfma_f32_16x16x32_bf16 v[140:143], v[100:103], v[180:183], v[140:143]
	v_mfma_f32_16x16x32_bf16 v[136:139], v[108:111], v[180:183], v[136:139]
	v_mfma_f32_16x16x32_bf16 v[124:127], v[100:103], v[188:191], v[124:127]
	v_mfma_f32_16x16x32_bf16 v[120:123], v[108:111], v[188:191], v[120:123]
	v_mfma_f32_16x16x32_bf16 v[92:95], v[100:103], v[196:199], v[92:95]
	v_mfma_f32_16x16x32_bf16 v[88:91], v[108:111], v[196:199], v[88:91]
	v_mfma_f32_16x16x32_bf16 v[76:79], v[100:103], v[218:221], v[76:79]
	v_mfma_f32_16x16x32_bf16 v[72:75], v[108:111], v[218:221], v[72:75]
	v_mfma_f32_16x16x32_bf16 v[140:143], v[104:107], v[184:187], v[140:143]
	v_mfma_f32_16x16x32_bf16 v[136:139], v[154:157], v[184:187], v[136:139]
	v_mfma_f32_16x16x32_bf16 v[124:127], v[104:107], v[192:195], v[124:127]
	v_mfma_f32_16x16x32_bf16 v[120:123], v[154:157], v[192:195], v[120:123]
	v_mfma_f32_16x16x32_bf16 v[92:95], v[104:107], v[200:203], v[92:95]
	v_mfma_f32_16x16x32_bf16 v[88:91], v[154:157], v[200:203], v[88:91]
	v_mfma_f32_16x16x32_bf16 v[76:79], v[104:107], v[232:235], v[76:79]
	v_mfma_f32_16x16x32_bf16 v[72:75], v[154:157], v[232:235], v[72:75]
	v_mfma_f32_16x16x32_bf16 v[132:135], v[164:167], v[180:183], v[132:135]
	v_mfma_f32_16x16x32_bf16 v[128:131], v[172:175], v[180:183], v[128:131]
	v_mfma_f32_16x16x32_bf16 v[116:119], v[164:167], v[188:191], v[116:119]
	v_mfma_f32_16x16x32_bf16 v[112:115], v[172:175], v[188:191], v[112:115]
	v_mfma_f32_16x16x32_bf16 v[84:87], v[164:167], v[196:199], v[84:87]
	v_mfma_f32_16x16x32_bf16 v[80:83], v[172:175], v[196:199], v[80:83]
	v_mfma_f32_16x16x32_bf16 v[68:71], v[164:167], v[218:221], v[68:71]
	v_mfma_f32_16x16x32_bf16 v[64:67], v[172:175], v[218:221], v[64:67]
	v_mfma_f32_16x16x32_bf16 v[132:135], v[168:171], v[184:187], v[132:135]
	v_mfma_f32_16x16x32_bf16 v[128:131], v[176:179], v[184:187], v[128:131]
	v_mfma_f32_16x16x32_bf16 v[116:119], v[168:171], v[192:195], v[116:119]
	v_mfma_f32_16x16x32_bf16 v[112:115], v[176:179], v[192:195], v[112:115]
	v_mfma_f32_16x16x32_bf16 v[84:87], v[168:171], v[200:203], v[84:87]
	v_mfma_f32_16x16x32_bf16 v[80:83], v[176:179], v[200:203], v[80:83]
	v_mfma_f32_16x16x32_bf16 v[68:71], v[168:171], v[232:235], v[68:71]
	v_mfma_f32_16x16x32_bf16 v[64:67], v[176:179], v[232:235], v[64:67]
	s_barrier
	s_add_i32 s78, s79, s23
	v_lshl_add_u64 v[158:159], s[44:45], 0, v[204:205]
	s_mov_b32 m0, s78
	ds_read_b128 v[180:183], v163 offset:16384
	ds_read_b128 v[184:187], v163 offset:17408
	ds_read_b128 v[188:191], v163 offset:18432
	ds_read_b128 v[192:195], v163 offset:19456
	ds_read_b128 v[196:199], v163 offset:20480
	ds_read_b128 v[200:203], v163 offset:21504
	ds_read_b128 v[218:221], v163 offset:22528
	ds_read_b128 v[232:235], v163 offset:23552
	global_load_lds_dwordx4 v[158:159], off
	s_add_i32 m0, s78, 0x2000
	s_add_u32 s78, s44, 0x80000
	v_lshl_add_u64 v[206:207], s[44:45], 0, v[144:145]
	s_addc_u32 s79, s45, 0
	s_add_i32 s53, s53, s23
	global_load_lds_dwordx4 v[206:207], off
	v_lshl_add_u64 v[208:209], s[78:79], 0, v[204:205]
	s_mov_b32 m0, s53
	s_nop 0
	global_load_lds_dwordx4 v[208:209], off
	v_lshl_add_u64 v[208:209], s[78:79], 0, v[144:145]
	s_add_i32 m0, s53, 0x2000
	s_nop 0
	global_load_lds_dwordx4 v[208:209], off
	s_waitcnt vmcnt(6)
	s_waitcnt lgkmcnt(0)
	s_barrier
	v_mfma_f32_16x16x32_bf16 v[60:63], v[100:103], v[180:183], v[60:63]
	v_mfma_f32_16x16x32_bf16 v[56:59], v[108:111], v[180:183], v[56:59]
	v_mfma_f32_16x16x32_bf16 v[48:51], v[100:103], v[188:191], v[48:51]
	v_mfma_f32_16x16x32_bf16 v[40:43], v[108:111], v[188:191], v[40:43]
	v_mfma_f32_16x16x32_bf16 v[32:35], v[100:103], v[196:199], v[32:35]
	v_mfma_f32_16x16x32_bf16 v[24:27], v[108:111], v[196:199], v[24:27]
	v_mfma_f32_16x16x32_bf16 v[16:19], v[100:103], v[218:221], v[16:19]
	v_mfma_f32_16x16x32_bf16 v[8:11], v[108:111], v[218:221], v[8:11]
	v_mfma_f32_16x16x32_bf16 v[60:63], v[104:107], v[184:187], v[60:63]
	v_mfma_f32_16x16x32_bf16 v[56:59], v[154:157], v[184:187], v[56:59]
	v_mfma_f32_16x16x32_bf16 v[48:51], v[104:107], v[192:195], v[48:51]
	v_mfma_f32_16x16x32_bf16 v[40:43], v[154:157], v[192:195], v[40:43]
	v_mfma_f32_16x16x32_bf16 v[32:35], v[104:107], v[200:203], v[32:35]
	v_mfma_f32_16x16x32_bf16 v[24:27], v[154:157], v[200:203], v[24:27]
	v_mfma_f32_16x16x32_bf16 v[16:19], v[104:107], v[232:235], v[16:19]
	v_mfma_f32_16x16x32_bf16 v[8:11], v[154:157], v[232:235], v[8:11]
	v_mfma_f32_16x16x32_bf16 v[52:55], v[164:167], v[180:183], v[52:55]
	v_mfma_f32_16x16x32_bf16 v[44:47], v[172:175], v[180:183], v[44:47]
	v_mfma_f32_16x16x32_bf16 v[36:39], v[164:167], v[188:191], v[36:39]
	v_mfma_f32_16x16x32_bf16 v[28:31], v[172:175], v[188:191], v[28:31]
	v_mfma_f32_16x16x32_bf16 v[20:23], v[164:167], v[196:199], v[20:23]
	v_mfma_f32_16x16x32_bf16 v[12:15], v[172:175], v[196:199], v[12:15]
	v_mfma_f32_16x16x32_bf16 v[4:7], v[164:167], v[218:221], v[4:7]
	v_mfma_f32_16x16x32_bf16 v[0:3], v[172:175], v[218:221], v[0:3]
	v_mfma_f32_16x16x32_bf16 v[52:55], v[168:171], v[184:187], v[52:55]
	v_mfma_f32_16x16x32_bf16 v[44:47], v[176:179], v[184:187], v[44:47]
	v_mfma_f32_16x16x32_bf16 v[36:39], v[168:171], v[192:195], v[36:39]
	v_mfma_f32_16x16x32_bf16 v[28:31], v[176:179], v[192:195], v[28:31]
	v_mfma_f32_16x16x32_bf16 v[20:23], v[168:171], v[200:203], v[20:23]
	v_mfma_f32_16x16x32_bf16 v[12:15], v[176:179], v[200:203], v[12:15]
	v_mfma_f32_16x16x32_bf16 v[4:7], v[168:171], v[232:235], v[4:7]
	v_mfma_f32_16x16x32_bf16 v[0:3], v[176:179], v[232:235], v[0:3]
	s_barrier
; #define PG8_STAGE(bufoff, gbase, voff) do { _Pragma("unroll") for (int _i = 0; _i < 2; ++_i) \
;         __builtin_amdgcn_global_load_lds((const unsigned*)((const char*)(gbase) + (voff)[_i]), (PG8_LAS unsigned*)(lds + (bufoff) + ldsw + _i * 8192), 16, 0, 0); } while (0)
; #define PG8_LDA(dst, b, h) do { _Pragma("unroll") for (int m = 0; m < 4; ++m) _Pragma("unroll") for (int k = 0; k < 2; ++k) dst[m][k] = *(const PG8_LAS bf16x8*)(lds + PG8_SA(b, h) + aoff + m * 2048 + k * 1024); } while (0)
; #define PG8_LDB(dst, b, h) do { _Pragma("unroll") for (int n = 0; n < 2; ++n) _Pragma("unroll") for (int k = 0; k < 2; ++k) dst[n][k] = *(const PG8_LAS bf16x8*)(lds + PG8_SB(b, h) + boff + n * 2048 + k * 1024); } while (0)
; #define PG8_MMA(ai, bj, At, Bt) do { __builtin_amdgcn_s_setprio(1); _Pragma("unroll") for (int m = 0; m < 4; ++m) _Pragma("unroll") for (int n = 0; n < 2; ++n) _Pragma("unroll") for (int k = 0; k < 2; ++k) \
;         acc[ai][bj][m][n] = __builtin_amdgcn_mfma_f32_16x16x32_bf16(Bt[n][k], At[m][k], acc[ai][bj][m][n], 0, 0, 0); __builtin_amdgcn_s_setprio(0); } while (0)
; #define PG8_WAIT_V(n) asm volatile("s_waitcnt vmcnt(" #n ")" ::: "memory")
; #define PG8_WAIT_L(n) asm volatile("s_waitcnt lgkmcnt(" #n ")" ::: "memory")
; #define PG8_BAR __builtin_amdgcn_s_barrier()
; #define PG8_SCHED __builtin_amdgcn_sched_barrier(0)
; template <class Epi, class Sched, bool ALIGN_EPI = false, bool SP2 = false>
; __device__ __forceinline__ void gemm_phase(PG8_LAS unsigned char* lds, const Gemm g, const Sched& S, const Epi& E) {
;     ...
;             PG8_LDB(B0, 1, 0); PG8_LDB(B1, 1, 1); PG8_SCHED; PG8_LDA(At, 1, 0); PG8_STAGE(PG8_SA(0, 0), a2, voffA); PG8_STAGE(PG8_SA(0, 1), a2 + hstep, voffA);
;             PG8_WAIT_V(8); PG8_WAIT_L(0); PG8_BAR; PG8_MMA(0, 0, At, B0); PG8_MMA(0, 1, At, B1); PG8_BAR; PG8_SCHED;
;             PG8_LDA(At, 1, 1); PG8_STAGE(PG8_SB(1, 0), b3, voffB); PG8_STAGE(PG8_SB(1, 1), b3 + hstep, voffB); (void)a3;
;             PG8_WAIT_V(6); PG8_WAIT_L(0); PG8_BAR; PG8_MMA(1, 0, At, B0); PG8_MMA(1, 1, At, B1); PG8_BAR; PG8_SCHED;
;     ...
;         if constexpr (ALIGN_EPI) { if (wr == 0) PG8_BAR; }
	s_add_i32 s53, 0, 0x18000
	s_add_i32 s92, 0, 0x1c000
	v_add_u32_e32 v154, s53, v161
	v_add_u32_e32 v176, s92, v161
	ds_read_b128 v[100:103], v154
	ds_read_b128 v[104:107], v154 offset:1024
	ds_read_b128 v[108:111], v154 offset:2048
	ds_read_b128 v[154:157], v154 offset:3072
	ds_read_b128 v[164:167], v176
	ds_read_b128 v[168:171], v176 offset:1024
	ds_read_b128 v[172:175], v176 offset:2048
	ds_read_b128 v[176:179], v176 offset:3072
	s_mov_b32 m0, s57
	v_lshl_add_u64 v[208:209], s[94:95], 0, v[148:149]
	s_add_u32 s78, s94, 0x80000
	ds_read_b128 v[180:183], v163 offset:32768
	ds_read_b128 v[184:187], v163 offset:33792
	ds_read_b128 v[188:191], v163 offset:34816
	ds_read_b128 v[192:195], v163 offset:35840
	ds_read_b128 v[196:199], v163 offset:36864
	ds_read_b128 v[200:203], v163 offset:37888
	ds_read_b128 v[218:221], v163 offset:38912
	ds_read_b128 v[232:235], v163 offset:39936
	global_load_lds_dwordx4 v[208:209], off
	v_lshl_add_u64 v[208:209], s[94:95], 0, v[146:147]
	s_mov_b32 m0, s84
	s_addc_u32 s79, s95, 0
	global_load_lds_dwordx4 v[208:209], off
	v_lshl_add_u64 v[208:209], s[78:79], 0, v[148:149]
	s_mov_b32 m0, s97
	s_nop 0
	global_load_lds_dwordx4 v[208:209], off
	v_lshl_add_u64 v[208:209], s[78:79], 0, v[146:147]
	s_mov_b32 m0, s34
	s_nop 0
	global_load_lds_dwordx4 v[208:209], off
	s_waitcnt vmcnt(8)
	s_waitcnt lgkmcnt(0)
	s_barrier
	v_mfma_f32_16x16x32_bf16 v[140:143], v[100:103], v[180:183], v[140:143]
	v_mfma_f32_16x16x32_bf16 v[136:139], v[108:111], v[180:183], v[136:139]
	v_mfma_f32_16x16x32_bf16 v[124:127], v[100:103], v[188:191], v[124:127]
	v_mfma_f32_16x16x32_bf16 v[120:123], v[108:111], v[188:191], v[120:123]
	v_mfma_f32_16x16x32_bf16 v[92:95], v[100:103], v[196:199], v[92:95]
	v_mfma_f32_16x16x32_bf16 v[88:91], v[108:111], v[196:199], v[88:91]
	v_mfma_f32_16x16x32_bf16 v[76:79], v[100:103], v[218:221], v[76:79]
	v_mfma_f32_16x16x32_bf16 v[72:75], v[108:111], v[218:221], v[72:75]
	v_mfma_f32_16x16x32_bf16 v[140:143], v[104:107], v[184:187], v[140:143]
	v_mfma_f32_16x16x32_bf16 v[136:139], v[154:157], v[184:187], v[136:139]
	v_mfma_f32_16x16x32_bf16 v[124:127], v[104:107], v[192:195], v[124:127]
	v_mfma_f32_16x16x32_bf16 v[120:123], v[154:157], v[192:195], v[120:123]
	v_mfma_f32_16x16x32_bf16 v[92:95], v[104:107], v[200:203], v[92:95]
	v_mfma_f32_16x16x32_bf16 v[88:91], v[154:157], v[200:203], v[88:91]
	v_mfma_f32_16x16x32_bf16 v[76:79], v[104:107], v[232:235], v[76:79]
	v_mfma_f32_16x16x32_bf16 v[72:75], v[154:157], v[232:235], v[72:75]
	v_mfma_f32_16x16x32_bf16 v[132:135], v[164:167], v[180:183], v[132:135]
	v_mfma_f32_16x16x32_bf16 v[128:131], v[172:175], v[180:183], v[128:131]
	v_mfma_f32_16x16x32_bf16 v[116:119], v[164:167], v[188:191], v[116:119]
	v_mfma_f32_16x16x32_bf16 v[112:115], v[172:175], v[188:191], v[112:115]
	v_mfma_f32_16x16x32_bf16 v[84:87], v[164:167], v[196:199], v[84:87]
	v_mfma_f32_16x16x32_bf16 v[80:83], v[172:175], v[196:199], v[80:83]
	v_mfma_f32_16x16x32_bf16 v[68:71], v[164:167], v[218:221], v[68:71]
	v_mfma_f32_16x16x32_bf16 v[64:67], v[172:175], v[218:221], v[64:67]
	v_mfma_f32_16x16x32_bf16 v[132:135], v[168:171], v[184:187], v[132:135]
	v_mfma_f32_16x16x32_bf16 v[128:131], v[176:179], v[184:187], v[128:131]
	v_mfma_f32_16x16x32_bf16 v[116:119], v[168:171], v[192:195], v[116:119]
	v_mfma_f32_16x16x32_bf16 v[112:115], v[176:179], v[192:195], v[112:115]
	v_mfma_f32_16x16x32_bf16 v[84:87], v[168:171], v[200:203], v[84:87]
	v_mfma_f32_16x16x32_bf16 v[80:83], v[176:179], v[200:203], v[80:83]
	v_mfma_f32_16x16x32_bf16 v[68:71], v[168:171], v[232:235], v[68:71]
	v_mfma_f32_16x16x32_bf16 v[64:67], v[176:179], v[232:235], v[64:67]
	s_barrier
	s_add_i32 s53, s53, s23
	v_lshl_add_u64 v[158:159], v[158:159], 0, s[26:27]
	s_mov_b32 m0, s53
	ds_read_b128 v[180:183], v163 offset:49152
	ds_read_b128 v[184:187], v163 offset:50176
	ds_read_b128 v[188:191], v163 offset:51200
	ds_read_b128 v[192:195], v163 offset:52224
	ds_read_b128 v[196:199], v163 offset:53248
	ds_read_b128 v[200:203], v163 offset:54272
	ds_read_b128 v[218:221], v163 offset:55296
	ds_read_b128 v[232:235], v163 offset:56320
	global_load_lds_dwordx4 v[158:159], off
	s_add_i32 m0, s53, 0x2000
	s_add_u32 s44, s44, 0x80080
	v_lshl_add_u64 v[158:159], v[206:207], 0, s[26:27]
	s_addc_u32 s45, s45, 0
	s_add_i32 s53, s92, s23
	global_load_lds_dwordx4 v[158:159], off
	v_lshl_add_u64 v[158:159], s[44:45], 0, v[204:205]
	s_mov_b32 m0, s53
	s_nop 0
	global_load_lds_dwordx4 v[158:159], off
	v_lshl_add_u64 v[158:159], s[44:45], 0, v[144:145]
	s_add_i32 m0, s53, 0x2000
	s_nop 0
	global_load_lds_dwordx4 v[158:159], off
	s_waitcnt vmcnt(6)
	s_waitcnt lgkmcnt(0)
	s_barrier
	v_mfma_f32_16x16x32_bf16 v[60:63], v[100:103], v[180:183], v[60:63]
	v_mfma_f32_16x16x32_bf16 v[56:59], v[108:111], v[180:183], v[56:59]
	v_mfma_f32_16x16x32_bf16 v[48:51], v[100:103], v[188:191], v[48:51]
	v_mfma_f32_16x16x32_bf16 v[40:43], v[108:111], v[188:191], v[40:43]
	v_mfma_f32_16x16x32_bf16 v[32:35], v[100:103], v[196:199], v[32:35]
	v_mfma_f32_16x16x32_bf16 v[24:27], v[108:111], v[196:199], v[24:27]
	v_mfma_f32_16x16x32_bf16 v[16:19], v[100:103], v[218:221], v[16:19]
	v_mfma_f32_16x16x32_bf16 v[8:11], v[108:111], v[218:221], v[8:11]
	v_mfma_f32_16x16x32_bf16 v[60:63], v[104:107], v[184:187], v[60:63]
	v_mfma_f32_16x16x32_bf16 v[56:59], v[154:157], v[184:187], v[56:59]
	v_mfma_f32_16x16x32_bf16 v[48:51], v[104:107], v[192:195], v[48:51]
	v_mfma_f32_16x16x32_bf16 v[40:43], v[154:157], v[192:195], v[40:43]
	v_mfma_f32_16x16x32_bf16 v[32:35], v[104:107], v[200:203], v[32:35]
	v_mfma_f32_16x16x32_bf16 v[24:27], v[154:157], v[200:203], v[24:27]
	v_mfma_f32_16x16x32_bf16 v[16:19], v[104:107], v[232:235], v[16:19]
	v_mfma_f32_16x16x32_bf16 v[8:11], v[154:157], v[232:235], v[8:11]
	v_mfma_f32_16x16x32_bf16 v[52:55], v[164:167], v[180:183], v[52:55]
	v_mfma_f32_16x16x32_bf16 v[44:47], v[172:175], v[180:183], v[44:47]
	v_mfma_f32_16x16x32_bf16 v[36:39], v[164:167], v[188:191], v[36:39]
	v_mfma_f32_16x16x32_bf16 v[28:31], v[172:175], v[188:191], v[28:31]
	v_mfma_f32_16x16x32_bf16 v[20:23], v[164:167], v[196:199], v[20:23]
	v_mfma_f32_16x16x32_bf16 v[12:15], v[172:175], v[196:199], v[12:15]
	v_mfma_f32_16x16x32_bf16 v[4:7], v[164:167], v[218:221], v[4:7]
	v_mfma_f32_16x16x32_bf16 v[0:3], v[172:175], v[218:221], v[0:3]
	v_mfma_f32_16x16x32_bf16 v[52:55], v[168:171], v[184:187], v[52:55]
	v_mfma_f32_16x16x32_bf16 v[44:47], v[176:179], v[184:187], v[44:47]
	v_mfma_f32_16x16x32_bf16 v[36:39], v[168:171], v[192:195], v[36:39]
	v_mfma_f32_16x16x32_bf16 v[28:31], v[176:179], v[192:195], v[28:31]
	v_mfma_f32_16x16x32_bf16 v[20:23], v[168:171], v[200:203], v[20:23]
	v_mfma_f32_16x16x32_bf16 v[12:15], v[176:179], v[200:203], v[12:15]
	v_mfma_f32_16x16x32_bf16 v[4:7], v[168:171], v[232:235], v[4:7]
	v_mfma_f32_16x16x32_bf16 v[0:3], v[176:179], v[232:235], v[0:3]
	s_barrier
	s_add_i32 s52, s52, 2
	s_add_u32 s88, s88, 0x100
	s_addc_u32 s89, s89, 0
	s_cmp_gt_u32 s52, 29
	s_cbranch_scc0 .LBB0_232
	s_setprio 0
	s_and_b64 vcc, exec, s[8:9]
	s_cbranch_vccz .LBB0_235
	s_barrier

; #define PG8_STAGE(bufoff, gbase, voff) do { _Pragma("unroll") for (int _i = 0; _i < 2; ++_i) \
;         __builtin_amdgcn_global_load_lds((const unsigned*)((const char*)(gbase) + (voff)[_i]), (PG8_LAS unsigned*)(lds + (bufoff) + ldsw + _i * 8192), 16, 0, 0); } while (0)
; #define PG8_LDA(dst, b, h) do { _Pragma("unroll") for (int m = 0; m < 4; ++m) _Pragma("unroll") for (int k = 0; k < 2; ++k) dst[m][k] = *(const PG8_LAS bf16x8*)(lds + PG8_SA(b, h) + aoff + m * 2048 + k * 1024); } while (0)
; #define PG8_LDB(dst, b, h) do { _Pragma("unroll") for (int n = 0; n < 2; ++n) _Pragma("unroll") for (int k = 0; k < 2; ++k) dst[n][k] = *(const PG8_LAS bf16x8*)(lds + PG8_SB(b, h) + boff + n * 2048 + k * 1024); } while (0)
; #define PG8_WAIT_V(n) asm volatile("s_waitcnt vmcnt(" #n ")" ::: "memory")
; #define PG8_WAIT_L(n) asm volatile("s_waitcnt lgkmcnt(" #n ")" ::: "memory")
; #define PG8_BAR __builtin_amdgcn_s_barrier()
; template <class Epi, class Sched, bool ALIGN_EPI = false, bool SP2 = false>
; __device__ __forceinline__ void gemm_phase(PG8_LAS unsigned char* lds, const Gemm g, const Sched& S, const Epi& E) {
;     ...
;         const bool has_next = S.next(ui + 1, nxt);
;         const char* nA = has_next ? (const char*)g.A + (size_t)nxt.pm * tstep : cA; const char* nB = has_next ? (const char*)g.Bt + (size_t)nxt.pn * tstep : cB;
;         for (int t = 0; t < nt; t += 2) {
;             const bool last = (t == nt - 2);
;             const char* a1 = cA + (size_t)(t + 1) * kstep;
;             const char* a2 = last ? nA : cA + (size_t)(t + 2) * kstep; const char* b2 = last ? nB : cB + (size_t)(t + 2) * kstep;
;             const char* a3 = a2 + kstep; const char* b3 = b2 + kstep;
;             if (last && has_next) S.a_ready(nxt);
;             if constexpr (SP2) {
;             PG8_LDB(B0, 0, 0); PG8_LDB(B1, 0, 1); PG8_SCHED; PG8_LDA(At, 0, 0); PG8_STAGE(PG8_SA(1, 0), a1, voffA); PG8_STAGE(PG8_SA(1, 1), a1 + hstep, voffA);
;             PG8_WAIT_V(8); PG8_WAIT_L(0); PG8_BAR; PG8_MMA(0, 0, At, B0); PG8_MMA(0, 1, At, B1); PG8_BAR; PG8_SCHED;
;     ...
; #pragma unroll
;         for (int a = 0; a < 2; ++a)
; #pragma unroll
;             for (int b = 0; b < 2; ++b)
; #pragma unroll
;                 for (int m = 0; m < 4; ++m)
; #pragma unroll
;                     for (int n = 0; n < 2; ++n) acc[a][b][m][n] = (f32x4){0.f, 0.f, 0.f, 0.f};
;         cur = nxt; cA = nA; cB = nB; ++ui;
.LBB0_425:
	s_ashr_i32 s47, s46, 31
	s_lshl_b64 s[52:53], s[46:47], 20
	s_add_u32 s72, s98, s52
	s_addc_u32 s73, s99, s53
	s_and_b64 s[52:53], s[38:39], exec
	s_cselect_b32 s47, s73, s17
	s_cselect_b32 s68, s72, s16
	s_ashr_i32 s43, s42, 31
	s_lshl_b64 s[52:53], s[42:43], 20
	s_add_u32 s76, s20, s52
	s_addc_u32 s77, s21, s53
	s_and_b64 s[52:53], s[38:39], exec
	s_cselect_b32 s43, s77, s45
	s_cselect_b32 s69, s76, s44
	s_add_u32 s70, s44, 0x100
	v_mov_b32_e32 v0, 0
	s_addc_u32 s71, s45, 0
	v_lshl_add_u64 v[138:139], s[16:17], 0, v[134:135]
	v_lshl_add_u64 v[140:141], s[16:17], 0, v[136:137]
	s_mov_b32 s52, -2
	s_mov_b64 s[88:89], 0
	v_mov_b32_e32 v1, v0
	v_mov_b32_e32 v2, v0
	v_mov_b32_e32 v3, v0
	v_mov_b32_e32 v4, v0
	v_mov_b32_e32 v5, v0
	v_mov_b32_e32 v6, v0
	v_mov_b32_e32 v7, v0
	v_mov_b32_e32 v8, v0
	v_mov_b32_e32 v9, v0
	v_mov_b32_e32 v10, v0
	v_mov_b32_e32 v11, v0
	v_mov_b32_e32 v16, v0
	v_mov_b32_e32 v17, v0
	v_mov_b32_e32 v18, v0
	v_mov_b32_e32 v19, v0
	v_mov_b32_e32 v24, v0
	v_mov_b32_e32 v25, v0
	v_mov_b32_e32 v26, v0
	v_mov_b32_e32 v27, v0
	v_mov_b32_e32 v32, v0
	v_mov_b32_e32 v33, v0
	v_mov_b32_e32 v34, v0
	v_mov_b32_e32 v35, v0
	v_mov_b32_e32 v40, v0
	v_mov_b32_e32 v41, v0
	v_mov_b32_e32 v42, v0
	v_mov_b32_e32 v43, v0
	v_mov_b32_e32 v48, v0
	v_mov_b32_e32 v49, v0
	v_mov_b32_e32 v50, v0
	v_mov_b32_e32 v51, v0
	v_mov_b32_e32 v12, v0
	v_mov_b32_e32 v13, v0
	v_mov_b32_e32 v14, v0
	v_mov_b32_e32 v15, v0
	v_mov_b32_e32 v20, v0
	v_mov_b32_e32 v21, v0
	v_mov_b32_e32 v22, v0
	v_mov_b32_e32 v23, v0
	v_mov_b32_e32 v28, v0
	v_mov_b32_e32 v29, v0
	v_mov_b32_e32 v30, v0
	v_mov_b32_e32 v31, v0
	v_mov_b32_e32 v36, v0
	v_mov_b32_e32 v37, v0
	v_mov_b32_e32 v38, v0
	v_mov_b32_e32 v39, v0
	v_mov_b32_e32 v44, v0
	v_mov_b32_e32 v45, v0
	v_mov_b32_e32 v46, v0
	v_mov_b32_e32 v47, v0
	v_mov_b32_e32 v52, v0
	v_mov_b32_e32 v53, v0
	v_mov_b32_e32 v54, v0
	v_mov_b32_e32 v55, v0
	v_mov_b32_e32 v56, v0
	v_mov_b32_e32 v57, v0
	v_mov_b32_e32 v58, v0
	v_mov_b32_e32 v59, v0
	v_mov_b32_e32 v60, v0
	v_mov_b32_e32 v61, v0
	v_mov_b32_e32 v62, v0
	v_mov_b32_e32 v63, v0
	v_mov_b32_e32 v64, v0
	v_mov_b32_e32 v65, v0
	v_mov_b32_e32 v66, v0
	v_mov_b32_e32 v67, v0
	v_mov_b32_e32 v68, v0
	v_mov_b32_e32 v69, v0
	v_mov_b32_e32 v70, v0
	v_mov_b32_e32 v71, v0
	v_mov_b32_e32 v72, v0
	v_mov_b32_e32 v73, v0
	v_mov_b32_e32 v74, v0
	v_mov_b32_e32 v75, v0
	v_mov_b32_e32 v80, v0
	v_mov_b32_e32 v81, v0
	v_mov_b32_e32 v82, v0
	v_mov_b32_e32 v83, v0
	v_mov_b32_e32 v88, v0
	v_mov_b32_e32 v89, v0
	v_mov_b32_e32 v90, v0
	v_mov_b32_e32 v91, v0
	v_mov_b32_e32 v96, v0
	v_mov_b32_e32 v97, v0
	v_mov_b32_e32 v98, v0
	v_mov_b32_e32 v99, v0
	v_mov_b32_e32 v104, v0
	v_mov_b32_e32 v105, v0
	v_mov_b32_e32 v106, v0
	v_mov_b32_e32 v107, v0
	v_mov_b32_e32 v112, v0
	v_mov_b32_e32 v113, v0
	v_mov_b32_e32 v114, v0
	v_mov_b32_e32 v115, v0
	v_mov_b32_e32 v76, v0
	v_mov_b32_e32 v77, v0
	v_mov_b32_e32 v78, v0
	v_mov_b32_e32 v79, v0
	v_mov_b32_e32 v84, v0
	v_mov_b32_e32 v85, v0
	v_mov_b32_e32 v86, v0
	v_mov_b32_e32 v87, v0
	v_mov_b32_e32 v92, v0
	v_mov_b32_e32 v93, v0
	v_mov_b32_e32 v94, v0
	v_mov_b32_e32 v95, v0
	v_mov_b32_e32 v100, v0
	v_mov_b32_e32 v101, v0
	v_mov_b32_e32 v102, v0
	v_mov_b32_e32 v103, v0
	v_mov_b32_e32 v108, v0
	v_mov_b32_e32 v109, v0
	v_mov_b32_e32 v110, v0
	v_mov_b32_e32 v111, v0
	v_mov_b32_e32 v116, v0
	v_mov_b32_e32 v117, v0
	v_mov_b32_e32 v118, v0
	v_mov_b32_e32 v119, v0
	v_mov_b32_e32 v120, v0
	v_mov_b32_e32 v121, v0
	v_mov_b32_e32 v122, v0
	v_mov_b32_e32 v123, v0
	v_mov_b32_e32 v124, v0
	v_mov_b32_e32 v125, v0
	v_mov_b32_e32 v126, v0
	v_mov_b32_e32 v127, v0
	s_cmp_eq_u64 s[6:7], 0
	s_cbranch_scc1 .Lg3_np
	s_setprio 1
.Lg3_np:
.LBB0_426:
	s_add_u32 s44, s16, s88
	s_addc_u32 s45, s17, s89
	s_add_u32 s53, s44, 0x100
	s_addc_u32 s78, s45, 0
	s_add_u32 s44, s70, s88
	s_addc_u32 s45, s71, s89
	s_add_i32 s79, 0, 0x10000
	s_cmpk_eq_i32 s88, 0xf00
	s_cselect_b32 s45, s43, s45
	s_cselect_b32 s44, s69, s44
	s_cselect_b32 s95, s47, s78
	s_cselect_b32 s94, s68, s53
	s_add_i32 s53, 0, 0x14000
	v_add_u32_e32 v158, s79, v143
	v_add_u32_e32 v174, s53, v143
	ds_read_b128 v[146:149], v158
	ds_read_b128 v[150:153], v158 offset:1024
	ds_read_b128 v[154:157], v158 offset:2048
	ds_read_b128 v[158:161], v158 offset:3072
	ds_read_b128 v[162:165], v174
	ds_read_b128 v[166:169], v174 offset:1024
	ds_read_b128 v[170:173], v174 offset:2048
	ds_read_b128 v[174:177], v174 offset:3072
	v_lshl_add_u64 v[202:203], v[138:139], 0, s[88:89]
	v_lshl_add_u64 v[222:223], v[202:203], 0, s[26:27]
	s_add_i32 m0, s23, 0x8000
	ds_read_b128 v[178:181], v145
	ds_read_b128 v[182:185], v145 offset:1024
	ds_read_b128 v[186:189], v145 offset:2048
	ds_read_b128 v[190:193], v145 offset:3072
	ds_read_b128 v[194:197], v145 offset:4096
	ds_read_b128 v[198:201], v145 offset:5120
	ds_read_b128 v[206:209], v145 offset:6144
	ds_read_b128 v[218:221], v145 offset:7168
	global_load_lds_dwordx4 v[222:223], off
	v_lshl_add_u64 v[222:223], v[140:141], 0, s[88:89]
	v_lshl_add_u64 v[232:233], v[222:223], 0, s[26:27]
	s_add_i32 m0, s23, 0xa000
	v_lshl_add_u64 v[202:203], v[202:203], 0, s[28:29]
	global_load_lds_dwordx4 v[232:233], off
	s_add_i32 m0, s23, 0xc000
	s_nop 0
	global_load_lds_dwordx4 v[202:203], off
	v_lshl_add_u64 v[202:203], v[222:223], 0, s[28:29]
	s_add_i32 m0, s23, 0xe000
	s_nop 0
	global_load_lds_dwordx4 v[202:203], off
	s_waitcnt vmcnt(8)
	s_waitcnt lgkmcnt(0)
	s_barrier
; #define PG8_STAGE(bufoff, gbase, voff) do { _Pragma("unroll") for (int _i = 0; _i < 2; ++_i) \
;         __builtin_amdgcn_global_load_lds((const unsigned*)((const char*)(gbase) + (voff)[_i]), (PG8_LAS unsigned*)(lds + (bufoff) + ldsw + _i * 8192), 16, 0, 0); } while (0)
; #define PG8_LDA(dst, b, h) do { _Pragma("unroll") for (int m = 0; m < 4; ++m) _Pragma("unroll") for (int k = 0; k < 2; ++k) dst[m][k] = *(const PG8_LAS bf16x8*)(lds + PG8_SA(b, h) + aoff + m * 2048 + k * 1024); } while (0)
; #define PG8_MMA(ai, bj, At, Bt) do { __builtin_amdgcn_s_setprio(1); _Pragma("unroll") for (int m = 0; m < 4; ++m) _Pragma("unroll") for (int n = 0; n < 2; ++n) _Pragma("unroll") for (int k = 0; k < 2; ++k) \
;         acc[ai][bj][m][n] = __builtin_amdgcn_mfma_f32_16x16x32_bf16(Bt[n][k], At[m][k], acc[ai][bj][m][n], 0, 0, 0); __builtin_amdgcn_s_setprio(0); } while (0)
; #define PG8_WAIT_V(n) asm volatile("s_waitcnt vmcnt(" #n ")" ::: "memory")
; #define PG8_WAIT_L(n) asm volatile("s_waitcnt lgkmcnt(" #n ")" ::: "memory")
; #define PG8_BAR __builtin_amdgcn_s_barrier()
; #define PG8_SCHED __builtin_amdgcn_sched_barrier(0)
; template <class Epi, class Sched, bool ALIGN_EPI = false, bool SP2 = false>
; __device__ __forceinline__ void gemm_phase(PG8_LAS unsigned char* lds, const Gemm g, const Sched& S, const Epi& E) {
;     ...
;             PG8_WAIT_V(8); PG8_WAIT_L(0); PG8_BAR; PG8_MMA(0, 0, At, B0); PG8_MMA(0, 1, At, B1); PG8_BAR; PG8_SCHED;
;             PG8_LDA(At, 0, 1); PG8_STAGE(PG8_SB(0, 0), b2, voffB); PG8_STAGE(PG8_SB(0, 1), b2 + hstep, voffB);
;             PG8_WAIT_V(6); PG8_WAIT_L(0); PG8_BAR; PG8_MMA(1, 0, At, B0); PG8_MMA(1, 1, At, B1); PG8_BAR; PG8_SCHED;
	v_mfma_f32_16x16x32_bf16 v[124:127], v[146:149], v[178:181], v[124:127]
	v_mfma_f32_16x16x32_bf16 v[120:123], v[154:157], v[178:181], v[120:123]
	v_mfma_f32_16x16x32_bf16 v[116:119], v[146:149], v[186:189], v[116:119]
	v_mfma_f32_16x16x32_bf16 v[108:111], v[154:157], v[186:189], v[108:111]
	v_mfma_f32_16x16x32_bf16 v[100:103], v[146:149], v[194:197], v[100:103]
	v_mfma_f32_16x16x32_bf16 v[92:95], v[154:157], v[194:197], v[92:95]
	v_mfma_f32_16x16x32_bf16 v[84:87], v[146:149], v[206:209], v[84:87]
	v_mfma_f32_16x16x32_bf16 v[76:79], v[154:157], v[206:209], v[76:79]
	v_mfma_f32_16x16x32_bf16 v[124:127], v[150:153], v[182:185], v[124:127]
	v_mfma_f32_16x16x32_bf16 v[120:123], v[158:161], v[182:185], v[120:123]
	v_mfma_f32_16x16x32_bf16 v[116:119], v[150:153], v[190:193], v[116:119]
	v_mfma_f32_16x16x32_bf16 v[108:111], v[158:161], v[190:193], v[108:111]
	v_mfma_f32_16x16x32_bf16 v[100:103], v[150:153], v[198:201], v[100:103]
	v_mfma_f32_16x16x32_bf16 v[92:95], v[158:161], v[198:201], v[92:95]
	v_mfma_f32_16x16x32_bf16 v[84:87], v[150:153], v[218:221], v[84:87]
	v_mfma_f32_16x16x32_bf16 v[76:79], v[158:161], v[218:221], v[76:79]
	v_mfma_f32_16x16x32_bf16 v[112:115], v[162:165], v[178:181], v[112:115]
	v_mfma_f32_16x16x32_bf16 v[104:107], v[170:173], v[178:181], v[104:107]
	v_mfma_f32_16x16x32_bf16 v[96:99], v[162:165], v[186:189], v[96:99]
	v_mfma_f32_16x16x32_bf16 v[88:91], v[170:173], v[186:189], v[88:91]
	v_mfma_f32_16x16x32_bf16 v[80:83], v[162:165], v[194:197], v[80:83]
	v_mfma_f32_16x16x32_bf16 v[72:75], v[170:173], v[194:197], v[72:75]
	v_mfma_f32_16x16x32_bf16 v[68:71], v[162:165], v[206:209], v[68:71]
	v_mfma_f32_16x16x32_bf16 v[64:67], v[170:173], v[206:209], v[64:67]
	v_mfma_f32_16x16x32_bf16 v[112:115], v[166:169], v[182:185], v[112:115]
	v_mfma_f32_16x16x32_bf16 v[104:107], v[174:177], v[182:185], v[104:107]
	v_mfma_f32_16x16x32_bf16 v[96:99], v[166:169], v[190:193], v[96:99]
	v_mfma_f32_16x16x32_bf16 v[88:91], v[174:177], v[190:193], v[88:91]
	v_mfma_f32_16x16x32_bf16 v[80:83], v[166:169], v[198:201], v[80:83]
	v_mfma_f32_16x16x32_bf16 v[72:75], v[174:177], v[198:201], v[72:75]
	v_mfma_f32_16x16x32_bf16 v[68:71], v[166:169], v[218:221], v[68:71]
	v_mfma_f32_16x16x32_bf16 v[64:67], v[174:177], v[218:221], v[64:67]
	s_barrier
	s_add_i32 s78, s79, s22
	v_lshl_add_u64 v[202:203], s[44:45], 0, v[204:205]
	s_mov_b32 m0, s78
	ds_read_b128 v[178:181], v145 offset:16384
	ds_read_b128 v[182:185], v145 offset:17408
	ds_read_b128 v[186:189], v145 offset:18432
	ds_read_b128 v[190:193], v145 offset:19456
	ds_read_b128 v[194:197], v145 offset:20480
	ds_read_b128 v[198:201], v145 offset:21504
	ds_read_b128 v[206:209], v145 offset:22528
	ds_read_b128 v[218:221], v145 offset:23552
	global_load_lds_dwordx4 v[202:203], off
	s_add_i32 m0, s78, 0x2000
	s_add_u32 s78, s44, 0x80000
	v_lshl_add_u64 v[222:223], s[44:45], 0, v[128:129]
	s_addc_u32 s79, s45, 0
	s_add_i32 s53, s53, s22
	global_load_lds_dwordx4 v[222:223], off
	v_lshl_add_u64 v[232:233], s[78:79], 0, v[204:205]
	s_mov_b32 m0, s53
	s_nop 0
	global_load_lds_dwordx4 v[232:233], off
	v_lshl_add_u64 v[232:233], s[78:79], 0, v[128:129]
	s_add_i32 m0, s53, 0x2000
	s_nop 0
	global_load_lds_dwordx4 v[232:233], off
	s_waitcnt vmcnt(6)
	s_waitcnt lgkmcnt(0)
	s_barrier
	v_mfma_f32_16x16x32_bf16 v[60:63], v[146:149], v[178:181], v[60:63]
	v_mfma_f32_16x16x32_bf16 v[56:59], v[154:157], v[178:181], v[56:59]
	v_mfma_f32_16x16x32_bf16 v[52:55], v[146:149], v[186:189], v[52:55]
	v_mfma_f32_16x16x32_bf16 v[44:47], v[154:157], v[186:189], v[44:47]
	v_mfma_f32_16x16x32_bf16 v[36:39], v[146:149], v[194:197], v[36:39]
	v_mfma_f32_16x16x32_bf16 v[28:31], v[154:157], v[194:197], v[28:31]
	v_mfma_f32_16x16x32_bf16 v[20:23], v[146:149], v[206:209], v[20:23]
	v_mfma_f32_16x16x32_bf16 v[12:15], v[154:157], v[206:209], v[12:15]
	v_mfma_f32_16x16x32_bf16 v[60:63], v[150:153], v[182:185], v[60:63]
	v_mfma_f32_16x16x32_bf16 v[56:59], v[158:161], v[182:185], v[56:59]
	v_mfma_f32_16x16x32_bf16 v[52:55], v[150:153], v[190:193], v[52:55]
	v_mfma_f32_16x16x32_bf16 v[44:47], v[158:161], v[190:193], v[44:47]
	v_mfma_f32_16x16x32_bf16 v[36:39], v[150:153], v[198:201], v[36:39]
	v_mfma_f32_16x16x32_bf16 v[28:31], v[158:161], v[198:201], v[28:31]
	v_mfma_f32_16x16x32_bf16 v[20:23], v[150:153], v[218:221], v[20:23]
	v_mfma_f32_16x16x32_bf16 v[12:15], v[158:161], v[218:221], v[12:15]
	v_mfma_f32_16x16x32_bf16 v[48:51], v[162:165], v[178:181], v[48:51]
	v_mfma_f32_16x16x32_bf16 v[40:43], v[170:173], v[178:181], v[40:43]
	v_mfma_f32_16x16x32_bf16 v[32:35], v[162:165], v[186:189], v[32:35]
	v_mfma_f32_16x16x32_bf16 v[24:27], v[170:173], v[186:189], v[24:27]
	v_mfma_f32_16x16x32_bf16 v[16:19], v[162:165], v[194:197], v[16:19]
	v_mfma_f32_16x16x32_bf16 v[8:11], v[170:173], v[194:197], v[8:11]
	v_mfma_f32_16x16x32_bf16 v[4:7], v[162:165], v[206:209], v[4:7]
	v_mfma_f32_16x16x32_bf16 v[0:3], v[170:173], v[206:209], v[0:3]
	v_mfma_f32_16x16x32_bf16 v[48:51], v[166:169], v[182:185], v[48:51]
	v_mfma_f32_16x16x32_bf16 v[40:43], v[174:177], v[182:185], v[40:43]
	v_mfma_f32_16x16x32_bf16 v[32:35], v[166:169], v[190:193], v[32:35]
	v_mfma_f32_16x16x32_bf16 v[24:27], v[174:177], v[190:193], v[24:27]
	v_mfma_f32_16x16x32_bf16 v[16:19], v[166:169], v[198:201], v[16:19]
	v_mfma_f32_16x16x32_bf16 v[8:11], v[174:177], v[198:201], v[8:11]
	v_mfma_f32_16x16x32_bf16 v[4:7], v[166:169], v[218:221], v[4:7]
	v_mfma_f32_16x16x32_bf16 v[0:3], v[174:177], v[218:221], v[0:3]
	s_barrier
; #define PG8_STAGE(bufoff, gbase, voff) do { _Pragma("unroll") for (int _i = 0; _i < 2; ++_i) \
;         __builtin_amdgcn_global_load_lds((const unsigned*)((const char*)(gbase) + (voff)[_i]), (PG8_LAS unsigned*)(lds + (bufoff) + ldsw + _i * 8192), 16, 0, 0); } while (0)
; #define PG8_LDA(dst, b, h) do { _Pragma("unroll") for (int m = 0; m < 4; ++m) _Pragma("unroll") for (int k = 0; k < 2; ++k) dst[m][k] = *(const PG8_LAS bf16x8*)(lds + PG8_SA(b, h) + aoff + m * 2048 + k * 1024); } while (0)
; #define PG8_LDB(dst, b, h) do { _Pragma("unroll") for (int n = 0; n < 2; ++n) _Pragma("unroll") for (int k = 0; k < 2; ++k) dst[n][k] = *(const PG8_LAS bf16x8*)(lds + PG8_SB(b, h) + boff + n * 2048 + k * 1024); } while (0)
; #define PG8_MMA(ai, bj, At, Bt) do { __builtin_amdgcn_s_setprio(1); _Pragma("unroll") for (int m = 0; m < 4; ++m) _Pragma("unroll") for (int n = 0; n < 2; ++n) _Pragma("unroll") for (int k = 0; k < 2; ++k) \
;         acc[ai][bj][m][n] = __builtin_amdgcn_mfma_f32_16x16x32_bf16(Bt[n][k], At[m][k], acc[ai][bj][m][n], 0, 0, 0); __builtin_amdgcn_s_setprio(0); } while (0)
; #define PG8_WAIT_V(n) asm volatile("s_waitcnt vmcnt(" #n ")" ::: "memory")
; #define PG8_WAIT_L(n) asm volatile("s_waitcnt lgkmcnt(" #n ")" ::: "memory")
; #define PG8_BAR __builtin_amdgcn_s_barrier()
; #define PG8_SCHED __builtin_amdgcn_sched_barrier(0)
; template <class Epi, class Sched, bool ALIGN_EPI = false, bool SP2 = false>
; __device__ __forceinline__ void gemm_phase(PG8_LAS unsigned char* lds, const Gemm g, const Sched& S, const Epi& E) {
;     ...
;             PG8_LDB(B0, 1, 0); PG8_LDB(B1, 1, 1); PG8_SCHED; PG8_LDA(At, 1, 0); PG8_STAGE(PG8_SA(0, 0), a2, voffA); PG8_STAGE(PG8_SA(0, 1), a2 + hstep, voffA);
;             PG8_WAIT_V(8); PG8_WAIT_L(0); PG8_BAR; PG8_MMA(0, 0, At, B0); PG8_MMA(0, 1, At, B1); PG8_BAR; PG8_SCHED;
;             PG8_LDA(At, 1, 1); PG8_STAGE(PG8_SB(1, 0), b3, voffB); PG8_STAGE(PG8_SB(1, 1), b3 + hstep, voffB); (void)a3;
;             PG8_WAIT_V(6); PG8_WAIT_L(0); PG8_BAR; PG8_MMA(1, 0, At, B0); PG8_MMA(1, 1, At, B1); PG8_BAR; PG8_SCHED;
;     ...
;         if constexpr (ALIGN_EPI) { if (wr == 0) PG8_BAR; }
	s_add_i32 s53, 0, 0x18000
	s_add_i32 s84, 0, 0x1c000
	v_add_u32_e32 v158, s53, v143
	v_add_u32_e32 v174, s84, v143
	ds_read_b128 v[146:149], v158
	ds_read_b128 v[150:153], v158 offset:1024
	ds_read_b128 v[154:157], v158 offset:2048
	ds_read_b128 v[158:161], v158 offset:3072
	ds_read_b128 v[162:165], v174
	ds_read_b128 v[166:169], v174 offset:1024
	ds_read_b128 v[170:173], v174 offset:2048
	ds_read_b128 v[174:177], v174 offset:3072
	s_mov_b32 m0, s23
	v_lshl_add_u64 v[232:233], s[94:95], 0, v[132:133]
	s_add_u32 s78, s94, 0x80000
	ds_read_b128 v[178:181], v145 offset:32768
	ds_read_b128 v[182:185], v145 offset:33792
	ds_read_b128 v[186:189], v145 offset:34816
	ds_read_b128 v[190:193], v145 offset:35840
	ds_read_b128 v[194:197], v145 offset:36864
	ds_read_b128 v[198:201], v145 offset:37888
	ds_read_b128 v[206:209], v145 offset:38912
	ds_read_b128 v[218:221], v145 offset:39936
	global_load_lds_dwordx4 v[232:233], off
	v_lshl_add_u64 v[232:233], s[94:95], 0, v[130:131]
	s_mov_b32 m0, s34
	s_addc_u32 s79, s95, 0
	global_load_lds_dwordx4 v[232:233], off
	v_lshl_add_u64 v[232:233], s[78:79], 0, v[132:133]
	s_mov_b32 m0, s35
	s_nop 0
	global_load_lds_dwordx4 v[232:233], off
	v_lshl_add_u64 v[232:233], s[78:79], 0, v[130:131]
	s_mov_b32 m0, s36
	s_nop 0
	global_load_lds_dwordx4 v[232:233], off
	s_waitcnt vmcnt(8)
	s_waitcnt lgkmcnt(0)
	s_barrier
	v_mfma_f32_16x16x32_bf16 v[124:127], v[146:149], v[178:181], v[124:127]
	v_mfma_f32_16x16x32_bf16 v[120:123], v[154:157], v[178:181], v[120:123]
	v_mfma_f32_16x16x32_bf16 v[116:119], v[146:149], v[186:189], v[116:119]
	v_mfma_f32_16x16x32_bf16 v[108:111], v[154:157], v[186:189], v[108:111]
	v_mfma_f32_16x16x32_bf16 v[100:103], v[146:149], v[194:197], v[100:103]
	v_mfma_f32_16x16x32_bf16 v[92:95], v[154:157], v[194:197], v[92:95]
	v_mfma_f32_16x16x32_bf16 v[84:87], v[146:149], v[206:209], v[84:87]
	v_mfma_f32_16x16x32_bf16 v[76:79], v[154:157], v[206:209], v[76:79]
	v_mfma_f32_16x16x32_bf16 v[124:127], v[150:153], v[182:185], v[124:127]
	v_mfma_f32_16x16x32_bf16 v[120:123], v[158:161], v[182:185], v[120:123]
	v_mfma_f32_16x16x32_bf16 v[116:119], v[150:153], v[190:193], v[116:119]
	v_mfma_f32_16x16x32_bf16 v[108:111], v[158:161], v[190:193], v[108:111]
	v_mfma_f32_16x16x32_bf16 v[100:103], v[150:153], v[198:201], v[100:103]
	v_mfma_f32_16x16x32_bf16 v[92:95], v[158:161], v[198:201], v[92:95]
	v_mfma_f32_16x16x32_bf16 v[84:87], v[150:153], v[218:221], v[84:87]
	v_mfma_f32_16x16x32_bf16 v[76:79], v[158:161], v[218:221], v[76:79]
	v_mfma_f32_16x16x32_bf16 v[112:115], v[162:165], v[178:181], v[112:115]
	v_mfma_f32_16x16x32_bf16 v[104:107], v[170:173], v[178:181], v[104:107]
	v_mfma_f32_16x16x32_bf16 v[96:99], v[162:165], v[186:189], v[96:99]
	v_mfma_f32_16x16x32_bf16 v[88:91], v[170:173], v[186:189], v[88:91]
	v_mfma_f32_16x16x32_bf16 v[80:83], v[162:165], v[194:197], v[80:83]
	v_mfma_f32_16x16x32_bf16 v[72:75], v[170:173], v[194:197], v[72:75]
	v_mfma_f32_16x16x32_bf16 v[68:71], v[162:165], v[206:209], v[68:71]
	v_mfma_f32_16x16x32_bf16 v[64:67], v[170:173], v[206:209], v[64:67]
	v_mfma_f32_16x16x32_bf16 v[112:115], v[166:169], v[182:185], v[112:115]
	v_mfma_f32_16x16x32_bf16 v[104:107], v[174:177], v[182:185], v[104:107]
	v_mfma_f32_16x16x32_bf16 v[96:99], v[166:169], v[190:193], v[96:99]
	v_mfma_f32_16x16x32_bf16 v[88:91], v[174:177], v[190:193], v[88:91]
	v_mfma_f32_16x16x32_bf16 v[80:83], v[166:169], v[198:201], v[80:83]
	v_mfma_f32_16x16x32_bf16 v[72:75], v[174:177], v[198:201], v[72:75]
	v_mfma_f32_16x16x32_bf16 v[68:71], v[166:169], v[218:221], v[68:71]
	v_mfma_f32_16x16x32_bf16 v[64:67], v[174:177], v[218:221], v[64:67]
	s_barrier
	s_add_i32 s53, s53, s22
	v_lshl_add_u64 v[202:203], v[202:203], 0, s[26:27]
	s_mov_b32 m0, s53
	ds_read_b128 v[178:181], v145 offset:49152
	ds_read_b128 v[182:185], v145 offset:50176
	ds_read_b128 v[186:189], v145 offset:51200
	ds_read_b128 v[190:193], v145 offset:52224
	ds_read_b128 v[194:197], v145 offset:53248
	ds_read_b128 v[198:201], v145 offset:54272
	ds_read_b128 v[206:209], v145 offset:55296
	ds_read_b128 v[218:221], v145 offset:56320
	global_load_lds_dwordx4 v[202:203], off
	s_add_i32 m0, s53, 0x2000
	s_add_u32 s44, s44, 0x80080
	v_lshl_add_u64 v[202:203], v[222:223], 0, s[26:27]
	s_addc_u32 s45, s45, 0
	s_add_i32 s53, s84, s22
	global_load_lds_dwordx4 v[202:203], off
	v_lshl_add_u64 v[202:203], s[44:45], 0, v[204:205]
	s_mov_b32 m0, s53
	s_nop 0
	global_load_lds_dwordx4 v[202:203], off
	v_lshl_add_u64 v[202:203], s[44:45], 0, v[128:129]
	s_add_i32 m0, s53, 0x2000
	s_nop 0
	global_load_lds_dwordx4 v[202:203], off
	s_waitcnt vmcnt(6)
	s_waitcnt lgkmcnt(0)
	s_barrier
	v_mfma_f32_16x16x32_bf16 v[60:63], v[146:149], v[178:181], v[60:63]
	v_mfma_f32_16x16x32_bf16 v[56:59], v[154:157], v[178:181], v[56:59]
	v_mfma_f32_16x16x32_bf16 v[52:55], v[146:149], v[186:189], v[52:55]
	v_mfma_f32_16x16x32_bf16 v[44:47], v[154:157], v[186:189], v[44:47]
	v_mfma_f32_16x16x32_bf16 v[36:39], v[146:149], v[194:197], v[36:39]
	v_mfma_f32_16x16x32_bf16 v[28:31], v[154:157], v[194:197], v[28:31]
	v_mfma_f32_16x16x32_bf16 v[20:23], v[146:149], v[206:209], v[20:23]
	v_mfma_f32_16x16x32_bf16 v[12:15], v[154:157], v[206:209], v[12:15]
	v_mfma_f32_16x16x32_bf16 v[60:63], v[150:153], v[182:185], v[60:63]
	v_mfma_f32_16x16x32_bf16 v[56:59], v[158:161], v[182:185], v[56:59]
	v_mfma_f32_16x16x32_bf16 v[52:55], v[150:153], v[190:193], v[52:55]
	v_mfma_f32_16x16x32_bf16 v[44:47], v[158:161], v[190:193], v[44:47]
	v_mfma_f32_16x16x32_bf16 v[36:39], v[150:153], v[198:201], v[36:39]
	v_mfma_f32_16x16x32_bf16 v[28:31], v[158:161], v[198:201], v[28:31]
	v_mfma_f32_16x16x32_bf16 v[20:23], v[150:153], v[218:221], v[20:23]
	v_mfma_f32_16x16x32_bf16 v[12:15], v[158:161], v[218:221], v[12:15]
	v_mfma_f32_16x16x32_bf16 v[48:51], v[162:165], v[178:181], v[48:51]
	v_mfma_f32_16x16x32_bf16 v[40:43], v[170:173], v[178:181], v[40:43]
	v_mfma_f32_16x16x32_bf16 v[32:35], v[162:165], v[186:189], v[32:35]
	v_mfma_f32_16x16x32_bf16 v[24:27], v[170:173], v[186:189], v[24:27]
	v_mfma_f32_16x16x32_bf16 v[16:19], v[162:165], v[194:197], v[16:19]
	v_mfma_f32_16x16x32_bf16 v[8:11], v[170:173], v[194:197], v[8:11]
	v_mfma_f32_16x16x32_bf16 v[4:7], v[162:165], v[206:209], v[4:7]
	v_mfma_f32_16x16x32_bf16 v[0:3], v[170:173], v[206:209], v[0:3]
	v_mfma_f32_16x16x32_bf16 v[48:51], v[166:169], v[182:185], v[48:51]
	v_mfma_f32_16x16x32_bf16 v[40:43], v[174:177], v[182:185], v[40:43]
	v_mfma_f32_16x16x32_bf16 v[32:35], v[166:169], v[190:193], v[32:35]
	v_mfma_f32_16x16x32_bf16 v[24:27], v[174:177], v[190:193], v[24:27]
	v_mfma_f32_16x16x32_bf16 v[16:19], v[166:169], v[198:201], v[16:19]
	v_mfma_f32_16x16x32_bf16 v[8:11], v[174:177], v[198:201], v[8:11]
	v_mfma_f32_16x16x32_bf16 v[4:7], v[166:169], v[218:221], v[4:7]
	v_mfma_f32_16x16x32_bf16 v[0:3], v[174:177], v[218:221], v[0:3]
	s_barrier
	s_add_i32 s52, s52, 2
	s_add_u32 s88, s88, 0x100
	s_addc_u32 s89, s89, 0
	s_cmp_gt_u32 s52, 29
	s_cbranch_scc0 .LBB0_426
	s_setprio 0
	s_and_b64 vcc, exec, s[10:11]
	s_cbranch_vccz .LBB0_429
	s_barrier

; #define PG8_STAGE(bufoff, gbase, voff) do { _Pragma("unroll") for (int _i = 0; _i < 2; ++_i) \
;         __builtin_amdgcn_global_load_lds((const unsigned*)((const char*)(gbase) + (voff)[_i]), (PG8_LAS unsigned*)(lds + (bufoff) + ldsw + _i * 8192), 16, 0, 0); } while (0)
; #define PG8_LDA(dst, b, h) do { _Pragma("unroll") for (int m = 0; m < 4; ++m) _Pragma("unroll") for (int k = 0; k < 2; ++k) dst[m][k] = *(const PG8_LAS bf16x8*)(lds + PG8_SA(b, h) + aoff + m * 2048 + k * 1024); } while (0)
; #define PG8_LDB(dst, b, h) do { _Pragma("unroll") for (int n = 0; n < 2; ++n) _Pragma("unroll") for (int k = 0; k < 2; ++k) dst[n][k] = *(const PG8_LAS bf16x8*)(lds + PG8_SB(b, h) + boff + n * 2048 + k * 1024); } while (0)
; #define PG8_WAIT_V(n) asm volatile("s_waitcnt vmcnt(" #n ")" ::: "memory")
; #define PG8_WAIT_L(n) asm volatile("s_waitcnt lgkmcnt(" #n ")" ::: "memory")
; #define PG8_BAR __builtin_amdgcn_s_barrier()
; template <class Epi, class Sched, bool ALIGN_EPI = false, bool SP2 = false>
; __device__ __forceinline__ void gemm_phase(PG8_LAS unsigned char* lds, const Gemm g, const Sched& S, const Epi& E) {
;     ...
;         const bool has_next = S.next(ui + 1, nxt);
;         const char* nA = has_next ? (const char*)g.A + (size_t)nxt.pm * tstep : cA; const char* nB = has_next ? (const char*)g.Bt + (size_t)nxt.pn * tstep : cB;
;         for (int t = 0; t < nt; t += 2) {
;             const bool last = (t == nt - 2);
;             const char* a1 = cA + (size_t)(t + 1) * kstep;
;             const char* a2 = last ? nA : cA + (size_t)(t + 2) * kstep; const char* b2 = last ? nB : cB + (size_t)(t + 2) * kstep;
;             const char* a3 = a2 + kstep; const char* b3 = b2 + kstep;
;             if (last && has_next) S.a_ready(nxt);
;             if constexpr (SP2) {
;             PG8_LDB(B0, 0, 0); PG8_LDB(B1, 0, 1); PG8_SCHED; PG8_LDA(At, 0, 0); PG8_STAGE(PG8_SA(1, 0), a1, voffA); PG8_STAGE(PG8_SA(1, 1), a1 + hstep, voffA);
;             PG8_WAIT_V(8); PG8_WAIT_L(0); PG8_BAR; PG8_MMA(0, 0, At, B0); PG8_MMA(0, 1, At, B1); PG8_BAR; PG8_SCHED;
;     ...
; #pragma unroll
;         for (int a = 0; a < 2; ++a)
; #pragma unroll
;             for (int b = 0; b < 2; ++b)
; #pragma unroll
;                 for (int m = 0; m < 4; ++m)
; #pragma unroll
;                     for (int n = 0; n < 2; ++n) acc[a][b][m][n] = (f32x4){0.f, 0.f, 0.f, 0.f};
;         cur = nxt; cA = nA; cB = nB; ++ui;
.LBB0_604:
	s_ashr_i32 s95, s94, 31
	s_lshl_b64 s[16:17], s[94:95], 20
	s_add_u32 s16, s20, s16
	s_addc_u32 s17, s21, s17
	s_and_b64 s[44:45], s[42:43], exec
	s_cselect_b32 s95, s17, s9
	s_cselect_b32 s70, s16, s8
	s_ashr_i32 s7, s6, 31
	s_lshl_b64 s[44:45], s[6:7], 20
	s_add_u32 s44, s22, s44
	s_addc_u32 s45, s23, s45
	s_and_b64 s[52:53], s[42:43], exec
	s_cselect_b32 s7, s45, s11
	s_cselect_b32 s71, s44, s10
	s_add_u32 s79, s10, 0x100
	v_mov_b32_e32 v0, 0
	v_lshl_add_u64 v[138:139], s[8:9], 0, v[134:135]
	v_lshl_add_u64 v[140:141], s[8:9], 0, v[136:137]
	s_addc_u32 s52, s11, 0
	s_mov_b32 s53, -2
	s_mov_b64 vcc, 0
	v_mov_b32_e32 v1, v0
	v_mov_b32_e32 v2, v0
	v_mov_b32_e32 v3, v0
	v_mov_b32_e32 v4, v0
	v_mov_b32_e32 v5, v0
	v_mov_b32_e32 v6, v0
	v_mov_b32_e32 v7, v0
	v_mov_b32_e32 v16, v0
	v_mov_b32_e32 v17, v0
	v_mov_b32_e32 v18, v0
	v_mov_b32_e32 v19, v0
	v_mov_b32_e32 v20, v0
	v_mov_b32_e32 v21, v0
	v_mov_b32_e32 v22, v0
	v_mov_b32_e32 v23, v0
	v_mov_b32_e32 v32, v0
	v_mov_b32_e32 v33, v0
	v_mov_b32_e32 v34, v0
	v_mov_b32_e32 v35, v0
	v_mov_b32_e32 v36, v0
	v_mov_b32_e32 v37, v0
	v_mov_b32_e32 v38, v0
	v_mov_b32_e32 v39, v0
	v_mov_b32_e32 v48, v0
	v_mov_b32_e32 v49, v0
	v_mov_b32_e32 v50, v0
	v_mov_b32_e32 v51, v0
	v_mov_b32_e32 v52, v0
	v_mov_b32_e32 v53, v0
	v_mov_b32_e32 v54, v0
	v_mov_b32_e32 v55, v0
	v_mov_b32_e32 v8, v0
	v_mov_b32_e32 v9, v0
	v_mov_b32_e32 v10, v0
	v_mov_b32_e32 v11, v0
	v_mov_b32_e32 v12, v0
	v_mov_b32_e32 v13, v0
	v_mov_b32_e32 v14, v0
	v_mov_b32_e32 v15, v0
	v_mov_b32_e32 v24, v0
	v_mov_b32_e32 v25, v0
	v_mov_b32_e32 v26, v0
	v_mov_b32_e32 v27, v0
	v_mov_b32_e32 v28, v0
	v_mov_b32_e32 v29, v0
	v_mov_b32_e32 v30, v0
	v_mov_b32_e32 v31, v0
	v_mov_b32_e32 v40, v0
	v_mov_b32_e32 v41, v0
	v_mov_b32_e32 v42, v0
	v_mov_b32_e32 v43, v0
	v_mov_b32_e32 v44, v0
	v_mov_b32_e32 v45, v0
	v_mov_b32_e32 v46, v0
	v_mov_b32_e32 v47, v0
	v_mov_b32_e32 v56, v0
	v_mov_b32_e32 v57, v0
	v_mov_b32_e32 v58, v0
	v_mov_b32_e32 v59, v0
	v_mov_b32_e32 v60, v0
	v_mov_b32_e32 v61, v0
	v_mov_b32_e32 v62, v0
	v_mov_b32_e32 v63, v0
	v_mov_b32_e32 v64, v0
	v_mov_b32_e32 v65, v0
	v_mov_b32_e32 v66, v0
	v_mov_b32_e32 v67, v0
	v_mov_b32_e32 v68, v0
	v_mov_b32_e32 v69, v0
	v_mov_b32_e32 v70, v0
	v_mov_b32_e32 v71, v0
	v_mov_b32_e32 v80, v0
	v_mov_b32_e32 v81, v0
	v_mov_b32_e32 v82, v0
	v_mov_b32_e32 v83, v0
	v_mov_b32_e32 v84, v0
	v_mov_b32_e32 v85, v0
	v_mov_b32_e32 v86, v0
	v_mov_b32_e32 v87, v0
	v_mov_b32_e32 v96, v0
	v_mov_b32_e32 v97, v0
	v_mov_b32_e32 v98, v0
	v_mov_b32_e32 v99, v0
	v_mov_b32_e32 v100, v0
	v_mov_b32_e32 v101, v0
	v_mov_b32_e32 v102, v0
	v_mov_b32_e32 v103, v0
	v_mov_b32_e32 v112, v0
	v_mov_b32_e32 v113, v0
	v_mov_b32_e32 v114, v0
	v_mov_b32_e32 v115, v0
	v_mov_b32_e32 v116, v0
	v_mov_b32_e32 v117, v0
	v_mov_b32_e32 v118, v0
	v_mov_b32_e32 v119, v0
	v_mov_b32_e32 v72, v0
	v_mov_b32_e32 v73, v0
	v_mov_b32_e32 v74, v0
	v_mov_b32_e32 v75, v0
	v_mov_b32_e32 v76, v0
	v_mov_b32_e32 v77, v0
	v_mov_b32_e32 v78, v0
	v_mov_b32_e32 v79, v0
	v_mov_b32_e32 v88, v0
	v_mov_b32_e32 v89, v0
	v_mov_b32_e32 v90, v0
	v_mov_b32_e32 v91, v0
	v_mov_b32_e32 v92, v0
	v_mov_b32_e32 v93, v0
	v_mov_b32_e32 v94, v0
	v_mov_b32_e32 v95, v0
	v_mov_b32_e32 v104, v0
	v_mov_b32_e32 v105, v0
	v_mov_b32_e32 v106, v0
	v_mov_b32_e32 v107, v0
	v_mov_b32_e32 v108, v0
	v_mov_b32_e32 v109, v0
	v_mov_b32_e32 v110, v0
	v_mov_b32_e32 v111, v0
	v_mov_b32_e32 v120, v0
	v_mov_b32_e32 v121, v0
	v_mov_b32_e32 v122, v0
	v_mov_b32_e32 v123, v0
	v_mov_b32_e32 v124, v0
	v_mov_b32_e32 v125, v0
	v_mov_b32_e32 v126, v0
	v_mov_b32_e32 v127, v0
	s_cmp_eq_u64 s[76:77], 0
	s_cbranch_scc1 .Lg4_np
	s_setprio 1
.Lg4_np:
.LBB0_605:
	s_add_u32 s10, s8, vcc_lo
	s_addc_u32 s11, s9, vcc_hi
	s_add_u32 s38, s10, 0x100
	s_addc_u32 s39, s11, 0
	s_add_u32 s10, s79, vcc_lo
	s_addc_u32 s11, s52, vcc_hi
	s_add_i32 s78, 0, 0x10000
	s_cmpk_eq_i32 vcc_lo, 0xf00
	s_cselect_b32 s11, s7, s11
	s_cselect_b32 s10, s71, s10
	s_cselect_b32 s69, s95, s39
	s_cselect_b32 s68, s70, s38
	s_add_i32 s92, 0, 0x14000
	v_add_u32_e32 v158, s78, v143
	v_add_u32_e32 v174, s92, v143
	ds_read_b128 v[146:149], v158
	ds_read_b128 v[150:153], v158 offset:1024
	ds_read_b128 v[154:157], v158 offset:2048
	ds_read_b128 v[158:161], v158 offset:3072
	ds_read_b128 v[162:165], v174
	ds_read_b128 v[166:169], v174 offset:1024
	ds_read_b128 v[170:173], v174 offset:2048
	ds_read_b128 v[174:177], v174 offset:3072
	v_lshl_add_u64 v[202:203], v[140:141], 0, vcc
	v_lshl_add_u64 v[222:223], v[202:203], 0, s[26:27]
	s_add_i32 m0, s37, 0x8000
	ds_read_b128 v[178:181], v145
	ds_read_b128 v[182:185], v145 offset:1024
	ds_read_b128 v[186:189], v145 offset:2048
	ds_read_b128 v[190:193], v145 offset:3072
	ds_read_b128 v[194:197], v145 offset:4096
	ds_read_b128 v[198:201], v145 offset:5120
	ds_read_b128 v[206:209], v145 offset:6144
	ds_read_b128 v[218:221], v145 offset:7168
	global_load_lds_dwordx4 v[222:223], off
	v_lshl_add_u64 v[222:223], v[138:139], 0, vcc
	v_lshl_add_u64 v[232:233], v[222:223], 0, s[26:27]
	s_add_i32 m0, s37, 0xa000
	v_lshl_add_u64 v[202:203], v[202:203], 0, s[28:29]
	global_load_lds_dwordx4 v[232:233], off
	s_add_i32 m0, s37, 0xc000
	s_nop 0
	global_load_lds_dwordx4 v[202:203], off
	v_lshl_add_u64 v[202:203], v[222:223], 0, s[28:29]
	s_add_i32 m0, s37, 0xe000
	s_nop 0
	global_load_lds_dwordx4 v[202:203], off
	s_waitcnt vmcnt(8)
	s_waitcnt lgkmcnt(0)
	s_barrier
; #define PG8_STAGE(bufoff, gbase, voff) do { _Pragma("unroll") for (int _i = 0; _i < 2; ++_i) \
;         __builtin_amdgcn_global_load_lds((const unsigned*)((const char*)(gbase) + (voff)[_i]), (PG8_LAS unsigned*)(lds + (bufoff) + ldsw + _i * 8192), 16, 0, 0); } while (0)
; #define PG8_LDA(dst, b, h) do { _Pragma("unroll") for (int m = 0; m < 4; ++m) _Pragma("unroll") for (int k = 0; k < 2; ++k) dst[m][k] = *(const PG8_LAS bf16x8*)(lds + PG8_SA(b, h) + aoff + m * 2048 + k * 1024); } while (0)
; #define PG8_MMA(ai, bj, At, Bt) do { __builtin_amdgcn_s_setprio(1); _Pragma("unroll") for (int m = 0; m < 4; ++m) _Pragma("unroll") for (int n = 0; n < 2; ++n) _Pragma("unroll") for (int k = 0; k < 2; ++k) \
;         acc[ai][bj][m][n] = __builtin_amdgcn_mfma_f32_16x16x32_bf16(Bt[n][k], At[m][k], acc[ai][bj][m][n], 0, 0, 0); __builtin_amdgcn_s_setprio(0); } while (0)
; #define PG8_WAIT_V(n) asm volatile("s_waitcnt vmcnt(" #n ")" ::: "memory")
; #define PG8_WAIT_L(n) asm volatile("s_waitcnt lgkmcnt(" #n ")" ::: "memory")
; #define PG8_BAR __builtin_amdgcn_s_barrier()
; #define PG8_SCHED __builtin_amdgcn_sched_barrier(0)
; template <class Epi, class Sched, bool ALIGN_EPI = false, bool SP2 = false>
; __device__ __forceinline__ void gemm_phase(PG8_LAS unsigned char* lds, const Gemm g, const Sched& S, const Epi& E) {
;     ...
;             PG8_WAIT_V(8); PG8_WAIT_L(0); PG8_BAR; PG8_MMA(0, 0, At, B0); PG8_MMA(0, 1, At, B1); PG8_BAR; PG8_SCHED;
;             PG8_LDA(At, 0, 1); PG8_STAGE(PG8_SB(0, 0), b2, voffB); PG8_STAGE(PG8_SB(0, 1), b2 + hstep, voffB);
;             PG8_WAIT_V(6); PG8_WAIT_L(0); PG8_BAR; PG8_MMA(1, 0, At, B0); PG8_MMA(1, 1, At, B1); PG8_BAR; PG8_SCHED;
	v_mfma_f32_16x16x32_bf16 v[124:127], v[146:149], v[178:181], v[124:127]
	v_mfma_f32_16x16x32_bf16 v[120:123], v[154:157], v[178:181], v[120:123]
	v_mfma_f32_16x16x32_bf16 v[108:111], v[146:149], v[186:189], v[108:111]
	v_mfma_f32_16x16x32_bf16 v[104:107], v[154:157], v[186:189], v[104:107]
	v_mfma_f32_16x16x32_bf16 v[92:95], v[146:149], v[194:197], v[92:95]
	v_mfma_f32_16x16x32_bf16 v[88:91], v[154:157], v[194:197], v[88:91]
	v_mfma_f32_16x16x32_bf16 v[76:79], v[146:149], v[206:209], v[76:79]
	v_mfma_f32_16x16x32_bf16 v[72:75], v[154:157], v[206:209], v[72:75]
	v_mfma_f32_16x16x32_bf16 v[124:127], v[150:153], v[182:185], v[124:127]
	v_mfma_f32_16x16x32_bf16 v[120:123], v[158:161], v[182:185], v[120:123]
	v_mfma_f32_16x16x32_bf16 v[108:111], v[150:153], v[190:193], v[108:111]
	v_mfma_f32_16x16x32_bf16 v[104:107], v[158:161], v[190:193], v[104:107]
	v_mfma_f32_16x16x32_bf16 v[92:95], v[150:153], v[198:201], v[92:95]
	v_mfma_f32_16x16x32_bf16 v[88:91], v[158:161], v[198:201], v[88:91]
	v_mfma_f32_16x16x32_bf16 v[76:79], v[150:153], v[218:221], v[76:79]
	v_mfma_f32_16x16x32_bf16 v[72:75], v[158:161], v[218:221], v[72:75]
	v_mfma_f32_16x16x32_bf16 v[116:119], v[162:165], v[178:181], v[116:119]
	v_mfma_f32_16x16x32_bf16 v[112:115], v[170:173], v[178:181], v[112:115]
	v_mfma_f32_16x16x32_bf16 v[100:103], v[162:165], v[186:189], v[100:103]
	v_mfma_f32_16x16x32_bf16 v[96:99], v[170:173], v[186:189], v[96:99]
	v_mfma_f32_16x16x32_bf16 v[84:87], v[162:165], v[194:197], v[84:87]
	v_mfma_f32_16x16x32_bf16 v[80:83], v[170:173], v[194:197], v[80:83]
	v_mfma_f32_16x16x32_bf16 v[68:71], v[162:165], v[206:209], v[68:71]
	v_mfma_f32_16x16x32_bf16 v[64:67], v[170:173], v[206:209], v[64:67]
	v_mfma_f32_16x16x32_bf16 v[116:119], v[166:169], v[182:185], v[116:119]
	v_mfma_f32_16x16x32_bf16 v[112:115], v[174:177], v[182:185], v[112:115]
	v_mfma_f32_16x16x32_bf16 v[100:103], v[166:169], v[190:193], v[100:103]
	v_mfma_f32_16x16x32_bf16 v[96:99], v[174:177], v[190:193], v[96:99]
	v_mfma_f32_16x16x32_bf16 v[84:87], v[166:169], v[198:201], v[84:87]
	v_mfma_f32_16x16x32_bf16 v[80:83], v[174:177], v[198:201], v[80:83]
	v_mfma_f32_16x16x32_bf16 v[68:71], v[166:169], v[218:221], v[68:71]
	v_mfma_f32_16x16x32_bf16 v[64:67], v[174:177], v[218:221], v[64:67]
	s_barrier
	s_add_i32 s38, s78, s36
	v_lshl_add_u64 v[202:203], s[10:11], 0, v[204:205]
	s_mov_b32 m0, s38
	ds_read_b128 v[178:181], v145 offset:16384
	ds_read_b128 v[182:185], v145 offset:17408
	ds_read_b128 v[186:189], v145 offset:18432
	ds_read_b128 v[190:193], v145 offset:19456
	ds_read_b128 v[194:197], v145 offset:20480
	ds_read_b128 v[198:201], v145 offset:21504
	ds_read_b128 v[206:209], v145 offset:22528
	ds_read_b128 v[218:221], v145 offset:23552
	global_load_lds_dwordx4 v[202:203], off
	s_add_i32 m0, s38, 0x2000
	s_add_u32 s38, s10, 0x80000
	v_lshl_add_u64 v[222:223], s[10:11], 0, v[128:129]
	s_addc_u32 s39, s11, 0
	s_add_i32 s78, s92, s36
	global_load_lds_dwordx4 v[222:223], off
	v_lshl_add_u64 v[232:233], s[38:39], 0, v[204:205]
	s_mov_b32 m0, s78
	s_nop 0
	global_load_lds_dwordx4 v[232:233], off
	v_lshl_add_u64 v[232:233], s[38:39], 0, v[128:129]
	s_add_i32 m0, s78, 0x2000
	s_nop 0
	global_load_lds_dwordx4 v[232:233], off
	s_waitcnt vmcnt(6)
	s_waitcnt lgkmcnt(0)
	s_barrier
	v_mfma_f32_16x16x32_bf16 v[60:63], v[146:149], v[178:181], v[60:63]
	v_mfma_f32_16x16x32_bf16 v[56:59], v[154:157], v[178:181], v[56:59]
	v_mfma_f32_16x16x32_bf16 v[44:47], v[146:149], v[186:189], v[44:47]
	v_mfma_f32_16x16x32_bf16 v[40:43], v[154:157], v[186:189], v[40:43]
	v_mfma_f32_16x16x32_bf16 v[28:31], v[146:149], v[194:197], v[28:31]
	v_mfma_f32_16x16x32_bf16 v[24:27], v[154:157], v[194:197], v[24:27]
	v_mfma_f32_16x16x32_bf16 v[12:15], v[146:149], v[206:209], v[12:15]
	v_mfma_f32_16x16x32_bf16 v[8:11], v[154:157], v[206:209], v[8:11]
	v_mfma_f32_16x16x32_bf16 v[60:63], v[150:153], v[182:185], v[60:63]
	v_mfma_f32_16x16x32_bf16 v[56:59], v[158:161], v[182:185], v[56:59]
	v_mfma_f32_16x16x32_bf16 v[44:47], v[150:153], v[190:193], v[44:47]
	v_mfma_f32_16x16x32_bf16 v[40:43], v[158:161], v[190:193], v[40:43]
	v_mfma_f32_16x16x32_bf16 v[28:31], v[150:153], v[198:201], v[28:31]
	v_mfma_f32_16x16x32_bf16 v[24:27], v[158:161], v[198:201], v[24:27]
	v_mfma_f32_16x16x32_bf16 v[12:15], v[150:153], v[218:221], v[12:15]
	v_mfma_f32_16x16x32_bf16 v[8:11], v[158:161], v[218:221], v[8:11]
	v_mfma_f32_16x16x32_bf16 v[52:55], v[162:165], v[178:181], v[52:55]
	v_mfma_f32_16x16x32_bf16 v[48:51], v[170:173], v[178:181], v[48:51]
	v_mfma_f32_16x16x32_bf16 v[36:39], v[162:165], v[186:189], v[36:39]
	v_mfma_f32_16x16x32_bf16 v[32:35], v[170:173], v[186:189], v[32:35]
	v_mfma_f32_16x16x32_bf16 v[20:23], v[162:165], v[194:197], v[20:23]
	v_mfma_f32_16x16x32_bf16 v[16:19], v[170:173], v[194:197], v[16:19]
	v_mfma_f32_16x16x32_bf16 v[4:7], v[162:165], v[206:209], v[4:7]
	v_mfma_f32_16x16x32_bf16 v[0:3], v[170:173], v[206:209], v[0:3]
	v_mfma_f32_16x16x32_bf16 v[52:55], v[166:169], v[182:185], v[52:55]
	v_mfma_f32_16x16x32_bf16 v[48:51], v[174:177], v[182:185], v[48:51]
	v_mfma_f32_16x16x32_bf16 v[36:39], v[166:169], v[190:193], v[36:39]
	v_mfma_f32_16x16x32_bf16 v[32:35], v[174:177], v[190:193], v[32:35]
	v_mfma_f32_16x16x32_bf16 v[20:23], v[166:169], v[198:201], v[20:23]
	v_mfma_f32_16x16x32_bf16 v[16:19], v[174:177], v[198:201], v[16:19]
	v_mfma_f32_16x16x32_bf16 v[4:7], v[166:169], v[218:221], v[4:7]
	v_mfma_f32_16x16x32_bf16 v[0:3], v[174:177], v[218:221], v[0:3]
	s_barrier
; #define PG8_STAGE(bufoff, gbase, voff) do { _Pragma("unroll") for (int _i = 0; _i < 2; ++_i) \
;         __builtin_amdgcn_global_load_lds((const unsigned*)((const char*)(gbase) + (voff)[_i]), (PG8_LAS unsigned*)(lds + (bufoff) + ldsw + _i * 8192), 16, 0, 0); } while (0)
; #define PG8_LDA(dst, b, h) do { _Pragma("unroll") for (int m = 0; m < 4; ++m) _Pragma("unroll") for (int k = 0; k < 2; ++k) dst[m][k] = *(const PG8_LAS bf16x8*)(lds + PG8_SA(b, h) + aoff + m * 2048 + k * 1024); } while (0)
; #define PG8_LDB(dst, b, h) do { _Pragma("unroll") for (int n = 0; n < 2; ++n) _Pragma("unroll") for (int k = 0; k < 2; ++k) dst[n][k] = *(const PG8_LAS bf16x8*)(lds + PG8_SB(b, h) + boff + n * 2048 + k * 1024); } while (0)
; #define PG8_MMA(ai, bj, At, Bt) do { __builtin_amdgcn_s_setprio(1); _Pragma("unroll") for (int m = 0; m < 4; ++m) _Pragma("unroll") for (int n = 0; n < 2; ++n) _Pragma("unroll") for (int k = 0; k < 2; ++k) \
;         acc[ai][bj][m][n] = __builtin_amdgcn_mfma_f32_16x16x32_bf16(Bt[n][k], At[m][k], acc[ai][bj][m][n], 0, 0, 0); __builtin_amdgcn_s_setprio(0); } while (0)
; #define PG8_WAIT_V(n) asm volatile("s_waitcnt vmcnt(" #n ")" ::: "memory")
; #define PG8_WAIT_L(n) asm volatile("s_waitcnt lgkmcnt(" #n ")" ::: "memory")
; #define PG8_BAR __builtin_amdgcn_s_barrier()
; #define PG8_SCHED __builtin_amdgcn_sched_barrier(0)
; template <class Epi, class Sched, bool ALIGN_EPI = false, bool SP2 = false>
; __device__ __forceinline__ void gemm_phase(PG8_LAS unsigned char* lds, const Gemm g, const Sched& S, const Epi& E) {
;     ...
;             PG8_LDB(B0, 1, 0); PG8_LDB(B1, 1, 1); PG8_SCHED; PG8_LDA(At, 1, 0); PG8_STAGE(PG8_SA(0, 0), a2, voffA); PG8_STAGE(PG8_SA(0, 1), a2 + hstep, voffA);
;             PG8_WAIT_V(8); PG8_WAIT_L(0); PG8_BAR; PG8_MMA(0, 0, At, B0); PG8_MMA(0, 1, At, B1); PG8_BAR; PG8_SCHED;
;             PG8_LDA(At, 1, 1); PG8_STAGE(PG8_SB(1, 0), b3, voffB); PG8_STAGE(PG8_SB(1, 1), b3 + hstep, voffB); (void)a3;
;             PG8_WAIT_V(6); PG8_WAIT_L(0); PG8_BAR; PG8_MMA(1, 0, At, B0); PG8_MMA(1, 1, At, B1); PG8_BAR; PG8_SCHED;
;     ...
;         if constexpr (ALIGN_EPI) { if (wr == 0) PG8_BAR; }
	s_add_i32 s78, 0, 0x18000
	s_add_i32 s92, 0, 0x1c000
	v_add_u32_e32 v158, s78, v143
	v_add_u32_e32 v174, s92, v143
	ds_read_b128 v[146:149], v158
	ds_read_b128 v[150:153], v158 offset:1024
	ds_read_b128 v[154:157], v158 offset:2048
	ds_read_b128 v[158:161], v158 offset:3072
	ds_read_b128 v[162:165], v174
	ds_read_b128 v[166:169], v174 offset:1024
	ds_read_b128 v[170:173], v174 offset:2048
	ds_read_b128 v[174:177], v174 offset:3072
	s_mov_b32 m0, s37
	v_lshl_add_u64 v[232:233], s[68:69], 0, v[132:133]
	s_add_u32 s38, s68, 0x80000
	ds_read_b128 v[178:181], v145 offset:32768
	ds_read_b128 v[182:185], v145 offset:33792
	ds_read_b128 v[186:189], v145 offset:34816
	ds_read_b128 v[190:193], v145 offset:35840
	ds_read_b128 v[194:197], v145 offset:36864
	ds_read_b128 v[198:201], v145 offset:37888
	ds_read_b128 v[206:209], v145 offset:38912
	ds_read_b128 v[218:221], v145 offset:39936
	global_load_lds_dwordx4 v[232:233], off
	v_lshl_add_u64 v[232:233], s[68:69], 0, v[130:131]
	s_mov_b32 m0, s57
	s_addc_u32 s39, s69, 0
	global_load_lds_dwordx4 v[232:233], off
	v_lshl_add_u64 v[232:233], s[38:39], 0, v[132:133]
	s_mov_b32 m0, s75
	s_nop 0
	global_load_lds_dwordx4 v[232:233], off
	v_lshl_add_u64 v[232:233], s[38:39], 0, v[130:131]
	s_mov_b32 m0, s84
	s_nop 0
	global_load_lds_dwordx4 v[232:233], off
	s_waitcnt vmcnt(8)
	s_waitcnt lgkmcnt(0)
	s_barrier
	v_mfma_f32_16x16x32_bf16 v[124:127], v[146:149], v[178:181], v[124:127]
	v_mfma_f32_16x16x32_bf16 v[120:123], v[154:157], v[178:181], v[120:123]
	v_mfma_f32_16x16x32_bf16 v[108:111], v[146:149], v[186:189], v[108:111]
	v_mfma_f32_16x16x32_bf16 v[104:107], v[154:157], v[186:189], v[104:107]
	v_mfma_f32_16x16x32_bf16 v[92:95], v[146:149], v[194:197], v[92:95]
	v_mfma_f32_16x16x32_bf16 v[88:91], v[154:157], v[194:197], v[88:91]
	v_mfma_f32_16x16x32_bf16 v[76:79], v[146:149], v[206:209], v[76:79]
	v_mfma_f32_16x16x32_bf16 v[72:75], v[154:157], v[206:209], v[72:75]
	v_mfma_f32_16x16x32_bf16 v[124:127], v[150:153], v[182:185], v[124:127]
	v_mfma_f32_16x16x32_bf16 v[120:123], v[158:161], v[182:185], v[120:123]
	v_mfma_f32_16x16x32_bf16 v[108:111], v[150:153], v[190:193], v[108:111]
	v_mfma_f32_16x16x32_bf16 v[104:107], v[158:161], v[190:193], v[104:107]
	v_mfma_f32_16x16x32_bf16 v[92:95], v[150:153], v[198:201], v[92:95]
	v_mfma_f32_16x16x32_bf16 v[88:91], v[158:161], v[198:201], v[88:91]
	v_mfma_f32_16x16x32_bf16 v[76:79], v[150:153], v[218:221], v[76:79]
	v_mfma_f32_16x16x32_bf16 v[72:75], v[158:161], v[218:221], v[72:75]
	v_mfma_f32_16x16x32_bf16 v[116:119], v[162:165], v[178:181], v[116:119]
	v_mfma_f32_16x16x32_bf16 v[112:115], v[170:173], v[178:181], v[112:115]
	v_mfma_f32_16x16x32_bf16 v[100:103], v[162:165], v[186:189], v[100:103]
	v_mfma_f32_16x16x32_bf16 v[96:99], v[170:173], v[186:189], v[96:99]
	v_mfma_f32_16x16x32_bf16 v[84:87], v[162:165], v[194:197], v[84:87]
	v_mfma_f32_16x16x32_bf16 v[80:83], v[170:173], v[194:197], v[80:83]
	v_mfma_f32_16x16x32_bf16 v[68:71], v[162:165], v[206:209], v[68:71]
	v_mfma_f32_16x16x32_bf16 v[64:67], v[170:173], v[206:209], v[64:67]
	v_mfma_f32_16x16x32_bf16 v[116:119], v[166:169], v[182:185], v[116:119]
	v_mfma_f32_16x16x32_bf16 v[112:115], v[174:177], v[182:185], v[112:115]
	v_mfma_f32_16x16x32_bf16 v[100:103], v[166:169], v[190:193], v[100:103]
	v_mfma_f32_16x16x32_bf16 v[96:99], v[174:177], v[190:193], v[96:99]
	v_mfma_f32_16x16x32_bf16 v[84:87], v[166:169], v[198:201], v[84:87]
	v_mfma_f32_16x16x32_bf16 v[80:83], v[174:177], v[198:201], v[80:83]
	v_mfma_f32_16x16x32_bf16 v[68:71], v[166:169], v[218:221], v[68:71]
	v_mfma_f32_16x16x32_bf16 v[64:67], v[174:177], v[218:221], v[64:67]
	s_barrier
	s_add_i32 s38, s78, s36
	v_lshl_add_u64 v[202:203], v[202:203], 0, s[26:27]
	s_mov_b32 m0, s38
	ds_read_b128 v[178:181], v145 offset:49152
	ds_read_b128 v[182:185], v145 offset:50176
	ds_read_b128 v[186:189], v145 offset:51200
	ds_read_b128 v[190:193], v145 offset:52224
	ds_read_b128 v[194:197], v145 offset:53248
	ds_read_b128 v[198:201], v145 offset:54272
	ds_read_b128 v[206:209], v145 offset:55296
	ds_read_b128 v[218:221], v145 offset:56320
	global_load_lds_dwordx4 v[202:203], off
	s_add_i32 m0, s38, 0x2000
	s_add_u32 s10, s10, 0x80080
	v_lshl_add_u64 v[202:203], v[222:223], 0, s[26:27]
	s_addc_u32 s11, s11, 0
	s_add_i32 s38, s92, s36
	global_load_lds_dwordx4 v[202:203], off
	v_lshl_add_u64 v[202:203], s[10:11], 0, v[204:205]
	s_mov_b32 m0, s38
	s_nop 0
	global_load_lds_dwordx4 v[202:203], off
	v_lshl_add_u64 v[202:203], s[10:11], 0, v[128:129]
	s_add_i32 m0, s38, 0x2000
	s_nop 0
	global_load_lds_dwordx4 v[202:203], off
	s_waitcnt vmcnt(6)
	s_waitcnt lgkmcnt(0)
	s_barrier
	v_mfma_f32_16x16x32_bf16 v[60:63], v[146:149], v[178:181], v[60:63]
	v_mfma_f32_16x16x32_bf16 v[56:59], v[154:157], v[178:181], v[56:59]
	v_mfma_f32_16x16x32_bf16 v[44:47], v[146:149], v[186:189], v[44:47]
	v_mfma_f32_16x16x32_bf16 v[40:43], v[154:157], v[186:189], v[40:43]
	v_mfma_f32_16x16x32_bf16 v[28:31], v[146:149], v[194:197], v[28:31]
	v_mfma_f32_16x16x32_bf16 v[24:27], v[154:157], v[194:197], v[24:27]
	v_mfma_f32_16x16x32_bf16 v[12:15], v[146:149], v[206:209], v[12:15]
	v_mfma_f32_16x16x32_bf16 v[8:11], v[154:157], v[206:209], v[8:11]
	v_mfma_f32_16x16x32_bf16 v[60:63], v[150:153], v[182:185], v[60:63]
	v_mfma_f32_16x16x32_bf16 v[56:59], v[158:161], v[182:185], v[56:59]
	v_mfma_f32_16x16x32_bf16 v[44:47], v[150:153], v[190:193], v[44:47]
	v_mfma_f32_16x16x32_bf16 v[40:43], v[158:161], v[190:193], v[40:43]
	v_mfma_f32_16x16x32_bf16 v[28:31], v[150:153], v[198:201], v[28:31]
	v_mfma_f32_16x16x32_bf16 v[24:27], v[158:161], v[198:201], v[24:27]
	v_mfma_f32_16x16x32_bf16 v[12:15], v[150:153], v[218:221], v[12:15]
	v_mfma_f32_16x16x32_bf16 v[8:11], v[158:161], v[218:221], v[8:11]
	v_mfma_f32_16x16x32_bf16 v[52:55], v[162:165], v[178:181], v[52:55]
	v_mfma_f32_16x16x32_bf16 v[48:51], v[170:173], v[178:181], v[48:51]
	v_mfma_f32_16x16x32_bf16 v[36:39], v[162:165], v[186:189], v[36:39]
	v_mfma_f32_16x16x32_bf16 v[32:35], v[170:173], v[186:189], v[32:35]
	v_mfma_f32_16x16x32_bf16 v[20:23], v[162:165], v[194:197], v[20:23]
	v_mfma_f32_16x16x32_bf16 v[16:19], v[170:173], v[194:197], v[16:19]
	v_mfma_f32_16x16x32_bf16 v[4:7], v[162:165], v[206:209], v[4:7]
	v_mfma_f32_16x16x32_bf16 v[0:3], v[170:173], v[206:209], v[0:3]
	v_mfma_f32_16x16x32_bf16 v[52:55], v[166:169], v[182:185], v[52:55]
	v_mfma_f32_16x16x32_bf16 v[48:51], v[174:177], v[182:185], v[48:51]
	v_mfma_f32_16x16x32_bf16 v[36:39], v[166:169], v[190:193], v[36:39]
	v_mfma_f32_16x16x32_bf16 v[32:35], v[174:177], v[190:193], v[32:35]
	v_mfma_f32_16x16x32_bf16 v[20:23], v[166:169], v[198:201], v[20:23]
	v_mfma_f32_16x16x32_bf16 v[16:19], v[174:177], v[198:201], v[16:19]
	v_mfma_f32_16x16x32_bf16 v[4:7], v[166:169], v[218:221], v[4:7]
	v_mfma_f32_16x16x32_bf16 v[0:3], v[174:177], v[218:221], v[0:3]
	s_barrier
	s_add_i32 s53, s53, 2
	s_add_u32 vcc_lo, vcc_lo, 0x100
	s_addc_u32 vcc_hi, vcc_hi, 0
	s_cmp_gt_u32 s53, 29
	s_cbranch_scc0 .LBB0_605
	s_setprio 0
	s_and_b64 vcc, exec, s[4:5]
	s_cbranch_vccz .LBB0_608
	s_barrier

; #define PG8_STAGE(bufoff, gbase, voff) do { _Pragma("unroll") for (int _i = 0; _i < 2; ++_i) \
;         __builtin_amdgcn_global_load_lds((const unsigned*)((const char*)(gbase) + (voff)[_i]), (PG8_LAS unsigned*)(lds + (bufoff) + ldsw + _i * 8192), 16, 0, 0); } while (0)
; #define PG8_LDA(dst, b, h) do { _Pragma("unroll") for (int m = 0; m < 4; ++m) _Pragma("unroll") for (int k = 0; k < 2; ++k) dst[m][k] = *(const PG8_LAS bf16x8*)(lds + PG8_SA(b, h) + aoff + m * 2048 + k * 1024); } while (0)
; #define PG8_LDB(dst, b, h) do { _Pragma("unroll") for (int n = 0; n < 2; ++n) _Pragma("unroll") for (int k = 0; k < 2; ++k) dst[n][k] = *(const PG8_LAS bf16x8*)(lds + PG8_SB(b, h) + boff + n * 2048 + k * 1024); } while (0)
; #define PG8_WAIT_V(n) asm volatile("s_waitcnt vmcnt(" #n ")" ::: "memory")
; #define PG8_WAIT_L(n) asm volatile("s_waitcnt lgkmcnt(" #n ")" ::: "memory")
; #define PG8_BAR __builtin_amdgcn_s_barrier()
; template <class Epi, class Sched, bool ALIGN_EPI = false, bool SP2 = false>
; __device__ __forceinline__ void gemm_phase(PG8_LAS unsigned char* lds, const Gemm g, const Sched& S, const Epi& E) {
;     ...
;         const bool has_next = S.next(ui + 1, nxt);
;         const char* nA = has_next ? (const char*)g.A + (size_t)nxt.pm * tstep : cA; const char* nB = has_next ? (const char*)g.Bt + (size_t)nxt.pn * tstep : cB;
;         for (int t = 0; t < nt; t += 2) {
;             const bool last = (t == nt - 2);
;             const char* a1 = cA + (size_t)(t + 1) * kstep;
;             const char* a2 = last ? nA : cA + (size_t)(t + 2) * kstep; const char* b2 = last ? nB : cB + (size_t)(t + 2) * kstep;
;             const char* a3 = a2 + kstep; const char* b3 = b2 + kstep;
;             if (last && has_next) S.a_ready(nxt);
;             if constexpr (SP2) {
;             PG8_LDB(B0, 0, 0); PG8_LDB(B1, 0, 1); PG8_SCHED; PG8_LDA(At, 0, 0); PG8_STAGE(PG8_SA(1, 0), a1, voffA); PG8_STAGE(PG8_SA(1, 1), a1 + hstep, voffA);
;             PG8_WAIT_V(8); PG8_WAIT_L(0); PG8_BAR; PG8_MMA(0, 0, At, B0); PG8_MMA(0, 1, At, B1); PG8_BAR; PG8_SCHED;
;     ...
; #pragma unroll
;         for (int a = 0; a < 2; ++a)
; #pragma unroll
;             for (int b = 0; b < 2; ++b)
; #pragma unroll
;                 for (int m = 0; m < 4; ++m)
; #pragma unroll
;                     for (int n = 0; n < 2; ++n) acc[a][b][m][n] = (f32x4){0.f, 0.f, 0.f, 0.f};
;         cur = nxt; cA = nA; cB = nB; ++ui;
.LBB0_701:
	s_ashr_i32 s47, s46, 31
	s_lshl_b64 s[38:39], s[46:47], 22
	s_add_u32 s72, s20, s38
	s_addc_u32 s73, s21, s39
	s_and_b64 s[38:39], s[40:41], exec
	s_cselect_b32 s47, s73, s17
	s_cselect_b32 s70, s72, s16
	s_ashr_i32 s43, s42, 31
	s_lshl_b64 s[38:39], s[42:43], 22
	s_add_u32 s76, s23, s38
	s_addc_u32 s77, s34, s39
	s_and_b64 s[38:39], s[40:41], exec
	s_cselect_b32 s43, s77, s45
	s_cselect_b32 s71, s76, s44
	s_add_u32 s97, s44, 0x100
	v_mov_b32_e32 v0, 0
	s_addc_u32 vcc_lo, s45, 0
	v_lshl_add_u64 v[138:139], s[16:17], 0, v[134:135]
	v_lshl_add_u64 v[140:141], s[16:17], 0, v[136:137]
	s_mov_b32 s52, -2
	s_mov_b64 s[88:89], 0
	v_mov_b32_e32 v1, v0
	v_mov_b32_e32 v2, v0
	v_mov_b32_e32 v3, v0
	v_mov_b32_e32 v4, v0
	v_mov_b32_e32 v5, v0
	v_mov_b32_e32 v6, v0
	v_mov_b32_e32 v7, v0
	v_mov_b32_e32 v8, v0
	v_mov_b32_e32 v9, v0
	v_mov_b32_e32 v10, v0
	v_mov_b32_e32 v11, v0
	v_mov_b32_e32 v16, v0
	v_mov_b32_e32 v17, v0
	v_mov_b32_e32 v18, v0
	v_mov_b32_e32 v19, v0
	v_mov_b32_e32 v24, v0
	v_mov_b32_e32 v25, v0
	v_mov_b32_e32 v26, v0
	v_mov_b32_e32 v27, v0
	v_mov_b32_e32 v32, v0
	v_mov_b32_e32 v33, v0
	v_mov_b32_e32 v34, v0
	v_mov_b32_e32 v35, v0
	v_mov_b32_e32 v40, v0
	v_mov_b32_e32 v41, v0
	v_mov_b32_e32 v42, v0
	v_mov_b32_e32 v43, v0
	v_mov_b32_e32 v48, v0
	v_mov_b32_e32 v49, v0
	v_mov_b32_e32 v50, v0
	v_mov_b32_e32 v51, v0
	v_mov_b32_e32 v12, v0
	v_mov_b32_e32 v13, v0
	v_mov_b32_e32 v14, v0
	v_mov_b32_e32 v15, v0
	v_mov_b32_e32 v20, v0
	v_mov_b32_e32 v21, v0
	v_mov_b32_e32 v22, v0
	v_mov_b32_e32 v23, v0
	v_mov_b32_e32 v28, v0
	v_mov_b32_e32 v29, v0
	v_mov_b32_e32 v30, v0
	v_mov_b32_e32 v31, v0
	v_mov_b32_e32 v36, v0
	v_mov_b32_e32 v37, v0
	v_mov_b32_e32 v38, v0
	v_mov_b32_e32 v39, v0
	v_mov_b32_e32 v44, v0
	v_mov_b32_e32 v45, v0
	v_mov_b32_e32 v46, v0
	v_mov_b32_e32 v47, v0
	v_mov_b32_e32 v52, v0
	v_mov_b32_e32 v53, v0
	v_mov_b32_e32 v54, v0
	v_mov_b32_e32 v55, v0
	v_mov_b32_e32 v56, v0
	v_mov_b32_e32 v57, v0
	v_mov_b32_e32 v58, v0
	v_mov_b32_e32 v59, v0
	v_mov_b32_e32 v60, v0
	v_mov_b32_e32 v61, v0
	v_mov_b32_e32 v62, v0
	v_mov_b32_e32 v63, v0
	v_mov_b32_e32 v64, v0
	v_mov_b32_e32 v65, v0
	v_mov_b32_e32 v66, v0
	v_mov_b32_e32 v67, v0
	v_mov_b32_e32 v68, v0
	v_mov_b32_e32 v69, v0
	v_mov_b32_e32 v70, v0
	v_mov_b32_e32 v71, v0
	v_mov_b32_e32 v72, v0
	v_mov_b32_e32 v73, v0
	v_mov_b32_e32 v74, v0
	v_mov_b32_e32 v75, v0
	v_mov_b32_e32 v80, v0
	v_mov_b32_e32 v81, v0
	v_mov_b32_e32 v82, v0
	v_mov_b32_e32 v83, v0
	v_mov_b32_e32 v88, v0
	v_mov_b32_e32 v89, v0
	v_mov_b32_e32 v90, v0
	v_mov_b32_e32 v91, v0
	v_mov_b32_e32 v96, v0
	v_mov_b32_e32 v97, v0
	v_mov_b32_e32 v98, v0
	v_mov_b32_e32 v99, v0
	v_mov_b32_e32 v104, v0
	v_mov_b32_e32 v105, v0
	v_mov_b32_e32 v106, v0
	v_mov_b32_e32 v107, v0
	v_mov_b32_e32 v112, v0
	v_mov_b32_e32 v113, v0
	v_mov_b32_e32 v114, v0
	v_mov_b32_e32 v115, v0
	v_mov_b32_e32 v76, v0
	v_mov_b32_e32 v77, v0
	v_mov_b32_e32 v78, v0
	v_mov_b32_e32 v79, v0
	v_mov_b32_e32 v84, v0
	v_mov_b32_e32 v85, v0
	v_mov_b32_e32 v86, v0
	v_mov_b32_e32 v87, v0
	v_mov_b32_e32 v92, v0
	v_mov_b32_e32 v93, v0
	v_mov_b32_e32 v94, v0
	v_mov_b32_e32 v95, v0
	v_mov_b32_e32 v100, v0
	v_mov_b32_e32 v101, v0
	v_mov_b32_e32 v102, v0
	v_mov_b32_e32 v103, v0
	v_mov_b32_e32 v108, v0
	v_mov_b32_e32 v109, v0
	v_mov_b32_e32 v110, v0
	v_mov_b32_e32 v111, v0
	v_mov_b32_e32 v116, v0
	v_mov_b32_e32 v117, v0
	v_mov_b32_e32 v118, v0
	v_mov_b32_e32 v119, v0
	v_mov_b32_e32 v120, v0
	v_mov_b32_e32 v121, v0
	v_mov_b32_e32 v122, v0
	v_mov_b32_e32 v123, v0
	v_mov_b32_e32 v124, v0
	v_mov_b32_e32 v125, v0
	v_mov_b32_e32 v126, v0
	v_mov_b32_e32 v127, v0
	s_cmp_eq_u64 s[6:7], 0
	s_cbranch_scc1 .Lg5_np
	s_setprio 1
.Lg5_np:
.LBB0_702:
	s_add_u32 s38, s16, s88
	s_addc_u32 s39, s17, s89
	s_add_u32 s38, s38, 0x100
	s_addc_u32 s39, s39, 0
	s_add_u32 s44, s97, s88
	s_addc_u32 s45, vcc_lo, s89
	s_add_i32 s53, 0, 0x10000
	s_cmpk_eq_i32 s88, 0x3f00
	s_cselect_b32 s45, s43, s45
	s_cselect_b32 s44, s71, s44
	s_cselect_b32 s69, s47, s39
	s_cselect_b32 s68, s70, s38
	s_add_i32 s78, 0, 0x14000
	v_add_u32_e32 v158, s53, v143
	v_add_u32_e32 v174, s78, v143
	ds_read_b128 v[146:149], v158
	ds_read_b128 v[150:153], v158 offset:1024
	ds_read_b128 v[154:157], v158 offset:2048
	ds_read_b128 v[158:161], v158 offset:3072
	ds_read_b128 v[162:165], v174
	ds_read_b128 v[166:169], v174 offset:1024
	ds_read_b128 v[170:173], v174 offset:2048
	ds_read_b128 v[174:177], v174 offset:3072
	v_lshl_add_u64 v[202:203], v[138:139], 0, s[88:89]
	v_lshl_add_u64 v[222:223], v[202:203], 0, s[26:27]
	s_add_i32 m0, s36, 0x8000
	ds_read_b128 v[178:181], v145
	ds_read_b128 v[182:185], v145 offset:1024
	ds_read_b128 v[186:189], v145 offset:2048
	ds_read_b128 v[190:193], v145 offset:3072
	ds_read_b128 v[194:197], v145 offset:4096
	ds_read_b128 v[198:201], v145 offset:5120
	ds_read_b128 v[206:209], v145 offset:6144
	ds_read_b128 v[218:221], v145 offset:7168
	global_load_lds_dwordx4 v[222:223], off
	v_lshl_add_u64 v[222:223], v[140:141], 0, s[88:89]
	v_lshl_add_u64 v[232:233], v[222:223], 0, s[26:27]
	s_add_i32 m0, s36, 0xa000
	v_lshl_add_u64 v[202:203], v[202:203], 0, s[90:91]
	global_load_lds_dwordx4 v[232:233], off
	s_add_i32 m0, s36, 0xc000
	s_nop 0
	global_load_lds_dwordx4 v[202:203], off
	v_lshl_add_u64 v[202:203], v[222:223], 0, s[90:91]
	s_add_i32 m0, s36, 0xe000
	s_nop 0
	global_load_lds_dwordx4 v[202:203], off
	s_waitcnt vmcnt(8)
	s_waitcnt lgkmcnt(0)
	s_barrier
; #define PG8_STAGE(bufoff, gbase, voff) do { _Pragma("unroll") for (int _i = 0; _i < 2; ++_i) \
;         __builtin_amdgcn_global_load_lds((const unsigned*)((const char*)(gbase) + (voff)[_i]), (PG8_LAS unsigned*)(lds + (bufoff) + ldsw + _i * 8192), 16, 0, 0); } while (0)
; #define PG8_LDA(dst, b, h) do { _Pragma("unroll") for (int m = 0; m < 4; ++m) _Pragma("unroll") for (int k = 0; k < 2; ++k) dst[m][k] = *(const PG8_LAS bf16x8*)(lds + PG8_SA(b, h) + aoff + m * 2048 + k * 1024); } while (0)
; #define PG8_MMA(ai, bj, At, Bt) do { __builtin_amdgcn_s_setprio(1); _Pragma("unroll") for (int m = 0; m < 4; ++m) _Pragma("unroll") for (int n = 0; n < 2; ++n) _Pragma("unroll") for (int k = 0; k < 2; ++k) \
;         acc[ai][bj][m][n] = __builtin_amdgcn_mfma_f32_16x16x32_bf16(Bt[n][k], At[m][k], acc[ai][bj][m][n], 0, 0, 0); __builtin_amdgcn_s_setprio(0); } while (0)
; #define PG8_WAIT_V(n) asm volatile("s_waitcnt vmcnt(" #n ")" ::: "memory")
; #define PG8_WAIT_L(n) asm volatile("s_waitcnt lgkmcnt(" #n ")" ::: "memory")
; #define PG8_BAR __builtin_amdgcn_s_barrier()
; #define PG8_SCHED __builtin_amdgcn_sched_barrier(0)
; template <class Epi, class Sched, bool ALIGN_EPI = false, bool SP2 = false>
; __device__ __forceinline__ void gemm_phase(PG8_LAS unsigned char* lds, const Gemm g, const Sched& S, const Epi& E) {
;     ...
;             PG8_WAIT_V(8); PG8_WAIT_L(0); PG8_BAR; PG8_MMA(0, 0, At, B0); PG8_MMA(0, 1, At, B1); PG8_BAR; PG8_SCHED;
;             PG8_LDA(At, 0, 1); PG8_STAGE(PG8_SB(0, 0), b2, voffB); PG8_STAGE(PG8_SB(0, 1), b2 + hstep, voffB);
;             PG8_WAIT_V(6); PG8_WAIT_L(0); PG8_BAR; PG8_MMA(1, 0, At, B0); PG8_MMA(1, 1, At, B1); PG8_BAR; PG8_SCHED;
	v_mfma_f32_16x16x32_bf16 v[124:127], v[146:149], v[178:181], v[124:127]
	v_mfma_f32_16x16x32_bf16 v[120:123], v[154:157], v[178:181], v[120:123]
	v_mfma_f32_16x16x32_bf16 v[116:119], v[146:149], v[186:189], v[116:119]
	v_mfma_f32_16x16x32_bf16 v[108:111], v[154:157], v[186:189], v[108:111]
	v_mfma_f32_16x16x32_bf16 v[100:103], v[146:149], v[194:197], v[100:103]
	v_mfma_f32_16x16x32_bf16 v[92:95], v[154:157], v[194:197], v[92:95]
	v_mfma_f32_16x16x32_bf16 v[84:87], v[146:149], v[206:209], v[84:87]
	v_mfma_f32_16x16x32_bf16 v[76:79], v[154:157], v[206:209], v[76:79]
	v_mfma_f32_16x16x32_bf16 v[124:127], v[150:153], v[182:185], v[124:127]
	v_mfma_f32_16x16x32_bf16 v[120:123], v[158:161], v[182:185], v[120:123]
	v_mfma_f32_16x16x32_bf16 v[116:119], v[150:153], v[190:193], v[116:119]
	v_mfma_f32_16x16x32_bf16 v[108:111], v[158:161], v[190:193], v[108:111]
	v_mfma_f32_16x16x32_bf16 v[100:103], v[150:153], v[198:201], v[100:103]
	v_mfma_f32_16x16x32_bf16 v[92:95], v[158:161], v[198:201], v[92:95]
	v_mfma_f32_16x16x32_bf16 v[84:87], v[150:153], v[218:221], v[84:87]
	v_mfma_f32_16x16x32_bf16 v[76:79], v[158:161], v[218:221], v[76:79]
	v_mfma_f32_16x16x32_bf16 v[112:115], v[162:165], v[178:181], v[112:115]
	v_mfma_f32_16x16x32_bf16 v[104:107], v[170:173], v[178:181], v[104:107]
	v_mfma_f32_16x16x32_bf16 v[96:99], v[162:165], v[186:189], v[96:99]
	v_mfma_f32_16x16x32_bf16 v[88:91], v[170:173], v[186:189], v[88:91]
	v_mfma_f32_16x16x32_bf16 v[80:83], v[162:165], v[194:197], v[80:83]
	v_mfma_f32_16x16x32_bf16 v[72:75], v[170:173], v[194:197], v[72:75]
	v_mfma_f32_16x16x32_bf16 v[68:71], v[162:165], v[206:209], v[68:71]
	v_mfma_f32_16x16x32_bf16 v[64:67], v[170:173], v[206:209], v[64:67]
	v_mfma_f32_16x16x32_bf16 v[112:115], v[166:169], v[182:185], v[112:115]
	v_mfma_f32_16x16x32_bf16 v[104:107], v[174:177], v[182:185], v[104:107]
	v_mfma_f32_16x16x32_bf16 v[96:99], v[166:169], v[190:193], v[96:99]
	v_mfma_f32_16x16x32_bf16 v[88:91], v[174:177], v[190:193], v[88:91]
	v_mfma_f32_16x16x32_bf16 v[80:83], v[166:169], v[198:201], v[80:83]
	v_mfma_f32_16x16x32_bf16 v[72:75], v[174:177], v[198:201], v[72:75]
	v_mfma_f32_16x16x32_bf16 v[68:71], v[166:169], v[218:221], v[68:71]
	v_mfma_f32_16x16x32_bf16 v[64:67], v[174:177], v[218:221], v[64:67]
	s_barrier
	s_add_i32 s38, s53, s35
	v_lshl_add_u64 v[202:203], s[44:45], 0, v[204:205]
	s_mov_b32 m0, s38
	ds_read_b128 v[178:181], v145 offset:16384
	ds_read_b128 v[182:185], v145 offset:17408
	ds_read_b128 v[186:189], v145 offset:18432
	ds_read_b128 v[190:193], v145 offset:19456
	ds_read_b128 v[194:197], v145 offset:20480
	ds_read_b128 v[198:201], v145 offset:21504
	ds_read_b128 v[206:209], v145 offset:22528
	ds_read_b128 v[218:221], v145 offset:23552
	global_load_lds_dwordx4 v[202:203], off
	s_add_i32 m0, s38, 0x2000
	s_add_u32 s38, s44, 0x200000
	v_lshl_add_u64 v[222:223], s[44:45], 0, v[128:129]
	s_addc_u32 s39, s45, 0
	s_add_i32 s53, s78, s35
	global_load_lds_dwordx4 v[222:223], off
	v_lshl_add_u64 v[232:233], s[38:39], 0, v[204:205]
	s_mov_b32 m0, s53
	s_nop 0
	global_load_lds_dwordx4 v[232:233], off
	v_lshl_add_u64 v[232:233], s[38:39], 0, v[128:129]
	s_add_i32 m0, s53, 0x2000
	s_nop 0
	global_load_lds_dwordx4 v[232:233], off
	s_waitcnt vmcnt(6)
	s_waitcnt lgkmcnt(0)
	s_barrier
	v_mfma_f32_16x16x32_bf16 v[60:63], v[146:149], v[178:181], v[60:63]
	v_mfma_f32_16x16x32_bf16 v[56:59], v[154:157], v[178:181], v[56:59]
	v_mfma_f32_16x16x32_bf16 v[52:55], v[146:149], v[186:189], v[52:55]
	v_mfma_f32_16x16x32_bf16 v[44:47], v[154:157], v[186:189], v[44:47]
	v_mfma_f32_16x16x32_bf16 v[36:39], v[146:149], v[194:197], v[36:39]
	v_mfma_f32_16x16x32_bf16 v[28:31], v[154:157], v[194:197], v[28:31]
	v_mfma_f32_16x16x32_bf16 v[20:23], v[146:149], v[206:209], v[20:23]
	v_mfma_f32_16x16x32_bf16 v[12:15], v[154:157], v[206:209], v[12:15]
	v_mfma_f32_16x16x32_bf16 v[60:63], v[150:153], v[182:185], v[60:63]
	v_mfma_f32_16x16x32_bf16 v[56:59], v[158:161], v[182:185], v[56:59]
	v_mfma_f32_16x16x32_bf16 v[52:55], v[150:153], v[190:193], v[52:55]
	v_mfma_f32_16x16x32_bf16 v[44:47], v[158:161], v[190:193], v[44:47]
	v_mfma_f32_16x16x32_bf16 v[36:39], v[150:153], v[198:201], v[36:39]
	v_mfma_f32_16x16x32_bf16 v[28:31], v[158:161], v[198:201], v[28:31]
	v_mfma_f32_16x16x32_bf16 v[20:23], v[150:153], v[218:221], v[20:23]
	v_mfma_f32_16x16x32_bf16 v[12:15], v[158:161], v[218:221], v[12:15]
	v_mfma_f32_16x16x32_bf16 v[48:51], v[162:165], v[178:181], v[48:51]
	v_mfma_f32_16x16x32_bf16 v[40:43], v[170:173], v[178:181], v[40:43]
	v_mfma_f32_16x16x32_bf16 v[32:35], v[162:165], v[186:189], v[32:35]
	v_mfma_f32_16x16x32_bf16 v[24:27], v[170:173], v[186:189], v[24:27]
	v_mfma_f32_16x16x32_bf16 v[16:19], v[162:165], v[194:197], v[16:19]
	v_mfma_f32_16x16x32_bf16 v[8:11], v[170:173], v[194:197], v[8:11]
	v_mfma_f32_16x16x32_bf16 v[4:7], v[162:165], v[206:209], v[4:7]
	v_mfma_f32_16x16x32_bf16 v[0:3], v[170:173], v[206:209], v[0:3]
	v_mfma_f32_16x16x32_bf16 v[48:51], v[166:169], v[182:185], v[48:51]
	v_mfma_f32_16x16x32_bf16 v[40:43], v[174:177], v[182:185], v[40:43]
	v_mfma_f32_16x16x32_bf16 v[32:35], v[166:169], v[190:193], v[32:35]
	v_mfma_f32_16x16x32_bf16 v[24:27], v[174:177], v[190:193], v[24:27]
	v_mfma_f32_16x16x32_bf16 v[16:19], v[166:169], v[198:201], v[16:19]
	v_mfma_f32_16x16x32_bf16 v[8:11], v[174:177], v[198:201], v[8:11]
	v_mfma_f32_16x16x32_bf16 v[4:7], v[166:169], v[218:221], v[4:7]
	v_mfma_f32_16x16x32_bf16 v[0:3], v[174:177], v[218:221], v[0:3]
	s_barrier
; #define PG8_STAGE(bufoff, gbase, voff) do { _Pragma("unroll") for (int _i = 0; _i < 2; ++_i) \
;         __builtin_amdgcn_global_load_lds((const unsigned*)((const char*)(gbase) + (voff)[_i]), (PG8_LAS unsigned*)(lds + (bufoff) + ldsw + _i * 8192), 16, 0, 0); } while (0)
; #define PG8_LDA(dst, b, h) do { _Pragma("unroll") for (int m = 0; m < 4; ++m) _Pragma("unroll") for (int k = 0; k < 2; ++k) dst[m][k] = *(const PG8_LAS bf16x8*)(lds + PG8_SA(b, h) + aoff + m * 2048 + k * 1024); } while (0)
; #define PG8_LDB(dst, b, h) do { _Pragma("unroll") for (int n = 0; n < 2; ++n) _Pragma("unroll") for (int k = 0; k < 2; ++k) dst[n][k] = *(const PG8_LAS bf16x8*)(lds + PG8_SB(b, h) + boff + n * 2048 + k * 1024); } while (0)
; #define PG8_MMA(ai, bj, At, Bt) do { __builtin_amdgcn_s_setprio(1); _Pragma("unroll") for (int m = 0; m < 4; ++m) _Pragma("unroll") for (int n = 0; n < 2; ++n) _Pragma("unroll") for (int k = 0; k < 2; ++k) \
;         acc[ai][bj][m][n] = __builtin_amdgcn_mfma_f32_16x16x32_bf16(Bt[n][k], At[m][k], acc[ai][bj][m][n], 0, 0, 0); __builtin_amdgcn_s_setprio(0); } while (0)
; #define PG8_WAIT_V(n) asm volatile("s_waitcnt vmcnt(" #n ")" ::: "memory")
; #define PG8_WAIT_L(n) asm volatile("s_waitcnt lgkmcnt(" #n ")" ::: "memory")
; #define PG8_BAR __builtin_amdgcn_s_barrier()
; #define PG8_SCHED __builtin_amdgcn_sched_barrier(0)
; template <class Epi, class Sched, bool ALIGN_EPI = false, bool SP2 = false>
; __device__ __forceinline__ void gemm_phase(PG8_LAS unsigned char* lds, const Gemm g, const Sched& S, const Epi& E) {
;     ...
;             PG8_LDB(B0, 1, 0); PG8_LDB(B1, 1, 1); PG8_SCHED; PG8_LDA(At, 1, 0); PG8_STAGE(PG8_SA(0, 0), a2, voffA); PG8_STAGE(PG8_SA(0, 1), a2 + hstep, voffA);
;             PG8_WAIT_V(8); PG8_WAIT_L(0); PG8_BAR; PG8_MMA(0, 0, At, B0); PG8_MMA(0, 1, At, B1); PG8_BAR; PG8_SCHED;
;             PG8_LDA(At, 1, 1); PG8_STAGE(PG8_SB(1, 0), b3, voffB); PG8_STAGE(PG8_SB(1, 1), b3 + hstep, voffB); (void)a3;
;             PG8_WAIT_V(6); PG8_WAIT_L(0); PG8_BAR; PG8_MMA(1, 0, At, B0); PG8_MMA(1, 1, At, B1); PG8_BAR; PG8_SCHED;
;     ...
;         if constexpr (ALIGN_EPI) { if (wr == 0) PG8_BAR; }
	s_add_i32 s53, 0, 0x18000
	s_add_i32 s78, 0, 0x1c000
	v_add_u32_e32 v158, s53, v143
	v_add_u32_e32 v174, s78, v143
	ds_read_b128 v[146:149], v158
	ds_read_b128 v[150:153], v158 offset:1024
	ds_read_b128 v[154:157], v158 offset:2048
	ds_read_b128 v[158:161], v158 offset:3072
	ds_read_b128 v[162:165], v174
	ds_read_b128 v[166:169], v174 offset:1024
	ds_read_b128 v[170:173], v174 offset:2048
	ds_read_b128 v[174:177], v174 offset:3072
	s_mov_b32 m0, s36
	v_lshl_add_u64 v[232:233], s[68:69], 0, v[132:133]
	s_add_u32 s38, s68, 0x200000
	ds_read_b128 v[178:181], v145 offset:32768
	ds_read_b128 v[182:185], v145 offset:33792
	ds_read_b128 v[186:189], v145 offset:34816
	ds_read_b128 v[190:193], v145 offset:35840
	ds_read_b128 v[194:197], v145 offset:36864
	ds_read_b128 v[198:201], v145 offset:37888
	ds_read_b128 v[206:209], v145 offset:38912
	ds_read_b128 v[218:221], v145 offset:39936
	global_load_lds_dwordx4 v[232:233], off
	v_lshl_add_u64 v[232:233], s[68:69], 0, v[130:131]
	s_mov_b32 m0, s37
	s_addc_u32 s39, s69, 0
	global_load_lds_dwordx4 v[232:233], off
	v_lshl_add_u64 v[232:233], s[38:39], 0, v[132:133]
	s_mov_b32 m0, s57
	s_nop 0
	global_load_lds_dwordx4 v[232:233], off
	v_lshl_add_u64 v[232:233], s[38:39], 0, v[130:131]
	s_mov_b32 m0, s75
	s_nop 0
	global_load_lds_dwordx4 v[232:233], off
	s_waitcnt vmcnt(8)
	s_waitcnt lgkmcnt(0)
	s_barrier
	v_mfma_f32_16x16x32_bf16 v[124:127], v[146:149], v[178:181], v[124:127]
	v_mfma_f32_16x16x32_bf16 v[120:123], v[154:157], v[178:181], v[120:123]
	v_mfma_f32_16x16x32_bf16 v[116:119], v[146:149], v[186:189], v[116:119]
	v_mfma_f32_16x16x32_bf16 v[108:111], v[154:157], v[186:189], v[108:111]
	v_mfma_f32_16x16x32_bf16 v[100:103], v[146:149], v[194:197], v[100:103]
	v_mfma_f32_16x16x32_bf16 v[92:95], v[154:157], v[194:197], v[92:95]
	v_mfma_f32_16x16x32_bf16 v[84:87], v[146:149], v[206:209], v[84:87]
	v_mfma_f32_16x16x32_bf16 v[76:79], v[154:157], v[206:209], v[76:79]
	v_mfma_f32_16x16x32_bf16 v[124:127], v[150:153], v[182:185], v[124:127]
	v_mfma_f32_16x16x32_bf16 v[120:123], v[158:161], v[182:185], v[120:123]
	v_mfma_f32_16x16x32_bf16 v[116:119], v[150:153], v[190:193], v[116:119]
	v_mfma_f32_16x16x32_bf16 v[108:111], v[158:161], v[190:193], v[108:111]
	v_mfma_f32_16x16x32_bf16 v[100:103], v[150:153], v[198:201], v[100:103]
	v_mfma_f32_16x16x32_bf16 v[92:95], v[158:161], v[198:201], v[92:95]
	v_mfma_f32_16x16x32_bf16 v[84:87], v[150:153], v[218:221], v[84:87]
	v_mfma_f32_16x16x32_bf16 v[76:79], v[158:161], v[218:221], v[76:79]
	v_mfma_f32_16x16x32_bf16 v[112:115], v[162:165], v[178:181], v[112:115]
	v_mfma_f32_16x16x32_bf16 v[104:107], v[170:173], v[178:181], v[104:107]
	v_mfma_f32_16x16x32_bf16 v[96:99], v[162:165], v[186:189], v[96:99]
	v_mfma_f32_16x16x32_bf16 v[88:91], v[170:173], v[186:189], v[88:91]
	v_mfma_f32_16x16x32_bf16 v[80:83], v[162:165], v[194:197], v[80:83]
	v_mfma_f32_16x16x32_bf16 v[72:75], v[170:173], v[194:197], v[72:75]
	v_mfma_f32_16x16x32_bf16 v[68:71], v[162:165], v[206:209], v[68:71]
	v_mfma_f32_16x16x32_bf16 v[64:67], v[170:173], v[206:209], v[64:67]
	v_mfma_f32_16x16x32_bf16 v[112:115], v[166:169], v[182:185], v[112:115]
	v_mfma_f32_16x16x32_bf16 v[104:107], v[174:177], v[182:185], v[104:107]
	v_mfma_f32_16x16x32_bf16 v[96:99], v[166:169], v[190:193], v[96:99]
	v_mfma_f32_16x16x32_bf16 v[88:91], v[174:177], v[190:193], v[88:91]
	v_mfma_f32_16x16x32_bf16 v[80:83], v[166:169], v[198:201], v[80:83]
	v_mfma_f32_16x16x32_bf16 v[72:75], v[174:177], v[198:201], v[72:75]
	v_mfma_f32_16x16x32_bf16 v[68:71], v[166:169], v[218:221], v[68:71]
	v_mfma_f32_16x16x32_bf16 v[64:67], v[174:177], v[218:221], v[64:67]
	s_barrier
	s_add_i32 s38, s53, s35
	v_lshl_add_u64 v[202:203], v[202:203], 0, s[26:27]
	s_mov_b32 m0, s38
	ds_read_b128 v[178:181], v145 offset:49152
	ds_read_b128 v[182:185], v145 offset:50176
	ds_read_b128 v[186:189], v145 offset:51200
	ds_read_b128 v[190:193], v145 offset:52224
	ds_read_b128 v[194:197], v145 offset:53248
	ds_read_b128 v[198:201], v145 offset:54272
	ds_read_b128 v[206:209], v145 offset:55296
	ds_read_b128 v[218:221], v145 offset:56320
	global_load_lds_dwordx4 v[202:203], off
	s_add_i32 m0, s38, 0x2000
	s_add_u32 s38, s44, 0x200080
	v_lshl_add_u64 v[202:203], v[222:223], 0, s[26:27]
	s_addc_u32 s39, s45, 0
	s_add_i32 s44, s78, s35
	global_load_lds_dwordx4 v[202:203], off
	v_lshl_add_u64 v[202:203], s[38:39], 0, v[204:205]
	s_mov_b32 m0, s44
	s_nop 0
	global_load_lds_dwordx4 v[202:203], off
	v_lshl_add_u64 v[202:203], s[38:39], 0, v[128:129]
	s_add_i32 m0, s44, 0x2000
	s_nop 0
	global_load_lds_dwordx4 v[202:203], off
	s_waitcnt vmcnt(6)
	s_waitcnt lgkmcnt(0)
	s_barrier
	v_mfma_f32_16x16x32_bf16 v[60:63], v[146:149], v[178:181], v[60:63]
	v_mfma_f32_16x16x32_bf16 v[56:59], v[154:157], v[178:181], v[56:59]
	v_mfma_f32_16x16x32_bf16 v[52:55], v[146:149], v[186:189], v[52:55]
	v_mfma_f32_16x16x32_bf16 v[44:47], v[154:157], v[186:189], v[44:47]
	v_mfma_f32_16x16x32_bf16 v[36:39], v[146:149], v[194:197], v[36:39]
	v_mfma_f32_16x16x32_bf16 v[28:31], v[154:157], v[194:197], v[28:31]
	v_mfma_f32_16x16x32_bf16 v[20:23], v[146:149], v[206:209], v[20:23]
	v_mfma_f32_16x16x32_bf16 v[12:15], v[154:157], v[206:209], v[12:15]
	v_mfma_f32_16x16x32_bf16 v[60:63], v[150:153], v[182:185], v[60:63]
	v_mfma_f32_16x16x32_bf16 v[56:59], v[158:161], v[182:185], v[56:59]
	v_mfma_f32_16x16x32_bf16 v[52:55], v[150:153], v[190:193], v[52:55]
	v_mfma_f32_16x16x32_bf16 v[44:47], v[158:161], v[190:193], v[44:47]
	v_mfma_f32_16x16x32_bf16 v[36:39], v[150:153], v[198:201], v[36:39]
	v_mfma_f32_16x16x32_bf16 v[28:31], v[158:161], v[198:201], v[28:31]
	v_mfma_f32_16x16x32_bf16 v[20:23], v[150:153], v[218:221], v[20:23]
	v_mfma_f32_16x16x32_bf16 v[12:15], v[158:161], v[218:221], v[12:15]
	v_mfma_f32_16x16x32_bf16 v[48:51], v[162:165], v[178:181], v[48:51]
	v_mfma_f32_16x16x32_bf16 v[40:43], v[170:173], v[178:181], v[40:43]
	v_mfma_f32_16x16x32_bf16 v[32:35], v[162:165], v[186:189], v[32:35]
	v_mfma_f32_16x16x32_bf16 v[24:27], v[170:173], v[186:189], v[24:27]
	v_mfma_f32_16x16x32_bf16 v[16:19], v[162:165], v[194:197], v[16:19]
	v_mfma_f32_16x16x32_bf16 v[8:11], v[170:173], v[194:197], v[8:11]
	v_mfma_f32_16x16x32_bf16 v[4:7], v[162:165], v[206:209], v[4:7]
	v_mfma_f32_16x16x32_bf16 v[0:3], v[170:173], v[206:209], v[0:3]
	v_mfma_f32_16x16x32_bf16 v[48:51], v[166:169], v[182:185], v[48:51]
	v_mfma_f32_16x16x32_bf16 v[40:43], v[174:177], v[182:185], v[40:43]
	v_mfma_f32_16x16x32_bf16 v[32:35], v[166:169], v[190:193], v[32:35]
	v_mfma_f32_16x16x32_bf16 v[24:27], v[174:177], v[190:193], v[24:27]
	v_mfma_f32_16x16x32_bf16 v[16:19], v[166:169], v[198:201], v[16:19]
	v_mfma_f32_16x16x32_bf16 v[8:11], v[174:177], v[198:201], v[8:11]
	v_mfma_f32_16x16x32_bf16 v[4:7], v[166:169], v[218:221], v[4:7]
	v_mfma_f32_16x16x32_bf16 v[0:3], v[174:177], v[218:221], v[0:3]
	s_barrier
	s_add_i32 s52, s52, 2
	s_add_u32 s88, s88, 0x100
	s_addc_u32 s89, s89, 0
	s_cmpk_gt_u32 s52, 0x7d
	s_cbranch_scc0 .LBB0_702
	s_setprio 0
	s_and_b64 vcc, exec, s[10:11]
	s_cbranch_vccz .LBB0_705
	s_barrier
